# v75 + scan loops: 32 VOP3-encoded v_mul_f32_e64 with plain VGPR operands re-encoded as 4-byte v_mul_f32_e32
# speedup vs baseline: 1.0014x; 1.0005x over previous
; __device__ __forceinline__ void scan_phase(const Frame& F, const bf16_t* Q, const bf16_t* K, const bf16_t* V, const bf16_t* PB, bf16_t* OF, bf16_t* OB, int half) {
;     ...
;                 {
;                     bf16x8 Rf[2];
; #pragma unroll
;                     for (int ks = 0; ks < 2; ++ks) { const f32x4 r0v = Rt[4 * p + 2 * ks], r1v = Rt[4 * p + 2 * ks + 1];
;                         const u32x4 wvv = {cvt_pk_bf16(r0v[0], r0v[1]), cvt_pk_bf16(r0v[2], r0v[3]), cvt_pk_bf16(r1v[0], r1v[1]), cvt_pk_bf16(r1v[2], r1v[3])};
;                         Rf[ks] = __builtin_bit_cast(bf16x8, wvv); }
;                     u32x4 qf[2][2];
;     ...
;                     SCAN_QREAD(0, 0);
; #pragma unroll
;                     for (int it = 0; it < 8; ++it) { if (it < 7) SCAN_QREAD((it + 1) & 1, it + 1);
; #pragma unroll
;                         for (int ks = 0; ks < 2; ++ks) Ot[it] = __builtin_amdgcn_mfma_f32_16x16x32_bf16(Rf[ks], __builtin_bit_cast(bf16x8, qf[it & 1][ks]), Ot[it], 0, 0, 0); }
;     ...
;                     __builtin_amdgcn_sched_group_barrier(0x100, 4, 0);
;                     __builtin_amdgcn_sched_group_barrier(0x100, 4, 0); __builtin_amdgcn_sched_group_barrier(0x8, 2, 0);
;                     __builtin_amdgcn_sched_group_barrier(0x100, 4, 0); __builtin_amdgcn_sched_group_barrier(0x8, 2, 0);
;                     __builtin_amdgcn_sched_group_barrier(0x100, 4, 0); __builtin_amdgcn_sched_group_barrier(0x8, 2, 0);
;                     __builtin_amdgcn_sched_group_barrier(0x100, 4, 0); __builtin_amdgcn_sched_group_barrier(0x8, 2, 0);
;                     __builtin_amdgcn_sched_group_barrier(0x100, 4, 0); __builtin_amdgcn_sched_group_barrier(0x8, 2, 0);
;                     __builtin_amdgcn_sched_group_barrier(0x100, 4, 0); __builtin_amdgcn_sched_group_barrier(0x8, 2, 0);
;                     __builtin_amdgcn_sched_group_barrier(0x100, 4, 0); __builtin_amdgcn_sched_group_barrier(0x8, 2, 0);
;                     __builtin_amdgcn_sched_group_barrier(0x8, 2, 0);
;                 }
;                 __builtin_amdgcn_sched_barrier(0);
;                 { s16x4 kl[2][4], kh[2][4];
;     ...
;                 SCAN_KREAD(0, 0);
; #pragma unroll
;                 for (int mt = 0; mt < 4; ++mt) { if (mt < 3) SCAN_KREAD((mt + 1) & 1, mt + 1);
;                     f32x4 acc = Rt[4 * p + mt] * c1;
; #pragma unroll
.LBB0_977:
	v_sub_u32_e32 v128, 0x80, v192
	v_cvt_f32_i32_e32 v238, v128
	v_cvt_pk_bf16_f32 v136, v48, v49
	v_cvt_pk_bf16_f32 v137, v50, v51
	v_cvt_pk_bf16_f32 v138, v52, v53
	v_cvt_pk_bf16_f32 v139, v54, v55
	v_cvt_pk_bf16_f32 v140, v56, v57
	v_cvt_pk_bf16_f32 v141, v58, v59
	v_cvt_pk_bf16_f32 v142, v60, v61
	v_cvt_pk_bf16_f32 v143, v62, v63
	ds_read_b64 v[128:129], v223 offset:16384
	ds_read_b64 v[130:131], v224 offset:16384
	ds_read_b64 v[132:133], v225 offset:16384
	ds_read_b64 v[134:135], v226 offset:16384
	ds_read_b64 v[156:157], v223 offset:18432
	ds_read_b64 v[158:159], v224 offset:18432
	ds_read_b64 v[194:195], v225 offset:18432
	ds_read_b64 v[196:197], v226 offset:18432
	s_waitcnt lgkmcnt(6)
	v_mfma_f32_16x16x32_bf16 v[96:99], v[136:139], v[128:131], v[96:99]
	s_waitcnt lgkmcnt(4)
	v_mfma_f32_16x16x32_bf16 v[128:131], v[140:143], v[132:135], v[96:99]
	s_nop 5
	ds_read_b64 v[96:97], v223 offset:20480
	ds_read_b64 v[98:99], v224 offset:20480
	ds_read_b64 v[234:235], v225 offset:20480
	ds_read_b64 v[236:237], v226 offset:20480
	s_waitcnt lgkmcnt(6)
	v_mfma_f32_16x16x32_bf16 v[100:103], v[136:139], v[156:159], v[100:103]
	s_waitcnt lgkmcnt(4)
	v_mfma_f32_16x16x32_bf16 v[132:135], v[140:143], v[194:197], v[100:103]
	s_nop 5
	ds_read_b64 v[100:101], v223 offset:22528
	ds_read_b64 v[102:103], v224 offset:22528
	ds_read_b64 v[156:157], v225 offset:22528
	ds_read_b64 v[158:159], v226 offset:22528
	s_waitcnt lgkmcnt(6)
	v_mfma_f32_16x16x32_bf16 v[96:99], v[136:139], v[96:99], v[104:107]
	s_waitcnt lgkmcnt(4)
	v_mfma_f32_16x16x32_bf16 v[104:107], v[140:143], v[234:237], v[96:99]
	s_nop 5
	ds_read_b64 v[96:97], v223 offset:24576
	ds_read_b64 v[98:99], v224 offset:24576
	ds_read_b64 v[194:195], v225 offset:24576
	ds_read_b64 v[196:197], v226 offset:24576
	s_waitcnt lgkmcnt(6)
	v_mfma_f32_16x16x32_bf16 v[100:103], v[136:139], v[100:103], v[108:111]
	s_waitcnt lgkmcnt(4)
	v_mfma_f32_16x16x32_bf16 v[108:111], v[140:143], v[156:159], v[100:103]
	s_nop 5
	ds_read_b64 v[100:101], v223 offset:26624
	ds_read_b64 v[102:103], v224 offset:26624
	ds_read_b64 v[156:157], v225 offset:26624
	ds_read_b64 v[158:159], v226 offset:26624
	s_waitcnt lgkmcnt(6)
	v_mfma_f32_16x16x32_bf16 v[96:99], v[136:139], v[96:99], v[112:115]
	s_waitcnt lgkmcnt(4)
	v_mfma_f32_16x16x32_bf16 v[112:115], v[140:143], v[194:197], v[96:99]
	s_nop 5
	ds_read_b64 v[96:97], v223 offset:28672
	ds_read_b64 v[98:99], v224 offset:28672
	ds_read_b64 v[194:195], v225 offset:28672
	ds_read_b64 v[196:197], v226 offset:28672
	s_waitcnt lgkmcnt(6)
	v_mfma_f32_16x16x32_bf16 v[100:103], v[136:139], v[100:103], v[116:119]
	s_waitcnt lgkmcnt(4)
	v_mfma_f32_16x16x32_bf16 v[100:103], v[140:143], v[156:159], v[100:103]
	s_nop 0
	ds_read_b64 v[116:117], v223 offset:30720
	ds_read_b64 v[118:119], v224 offset:30720
	ds_read_b64 v[156:157], v225 offset:30720
	ds_read_b64 v[158:159], v226 offset:30720
	s_waitcnt lgkmcnt(6)
	v_mfma_f32_16x16x32_bf16 v[96:99], v[136:139], v[96:99], v[120:123]
	s_waitcnt lgkmcnt(4)
	v_mfma_f32_16x16x32_bf16 v[96:99], v[140:143], v[194:197], v[96:99]
	s_waitcnt lgkmcnt(2)
	v_mfma_f32_16x16x32_bf16 v[116:119], v[136:139], v[116:119], v[124:127]
	s_waitcnt lgkmcnt(0)
	v_mfma_f32_16x16x32_bf16 v[116:119], v[140:143], v[156:159], v[116:119]
	ds_read_b64_tr_b16 v[120:121], v227 offset:49152
	ds_read_b64_tr_b16 v[122:123], v228 offset:49664
	ds_read_b64_tr_b16 v[124:125], v227 offset:53248
	ds_read_b64_tr_b16 v[126:127], v228 offset:53760
	ds_read_b64_tr_b16 v[136:137], v227 offset:57344
	ds_read_b64_tr_b16 v[138:139], v228 offset:57856
	v_mul_f32_e32 v50, v144, v50
	v_mul_f32_e32 v51, v145, v51
	v_mul_f32_e32 v48, v146, v48
	v_mul_f32_e32 v49, v147, v49
	ds_read_b64_tr_b16 v[140:141], v227 offset:61440
	ds_read_b64_tr_b16 v[142:143], v228 offset:61952
	ds_read_b64_tr_b16 v[156:157], v229 offset:49152
	ds_read_b64_tr_b16 v[158:159], v230 offset:49664
	ds_read_b64_tr_b16 v[194:195], v229 offset:53248
	ds_read_b64_tr_b16 v[196:197], v230 offset:53760
	ds_read_b64_tr_b16 v[224:225], v229 offset:57344
	ds_read_b64_tr_b16 v[226:227], v230 offset:57856
	ds_read_b64_tr_b16 v[234:235], v229 offset:61440
	ds_read_b64_tr_b16 v[236:237], v230 offset:61952
	s_waitcnt lgkmcnt(14)
	v_mfma_f32_16x16x32_bf16 v[48:51], v[120:123], v[72:75], v[48:51]
	v_mul_f32_e32 v54, v144, v54
	v_mul_f32_e32 v55, v145, v55
	v_mul_f32_e32 v52, v146, v52
	v_mul_f32_e32 v53, v147, v53
	v_mul_f32_e32 v58, v144, v58
	v_mul_f32_e32 v59, v145, v59
	s_waitcnt lgkmcnt(12)
	v_mfma_f32_16x16x32_bf16 v[48:51], v[124:127], v[80:83], v[48:51]
	v_mul_f32_e32 v56, v146, v56
	v_mul_f32_e32 v57, v147, v57
	v_mul_f32_e32 v62, v144, v62
	v_mul_f32_e32 v63, v145, v63
	v_mul_f32_e32 v60, v146, v60
	v_mul_f32_e32 v61, v147, v61
	s_waitcnt lgkmcnt(10)
	v_mfma_f32_16x16x32_bf16 v[48:51], v[136:139], v[88:91], v[48:51]
	s_add_u32 s12, s23, s40
	v_lshl_add_u32 v192, v192, 12, v213
	s_addc_u32 s13, s92, s41
	s_waitcnt lgkmcnt(8)
	v_mfma_f32_16x16x32_bf16 v[48:51], v[140:143], v[92:95], v[48:51]
	ds_read_b64_tr_b16 v[120:121], v231 offset:49152
	ds_read_b64_tr_b16 v[122:123], v232 offset:49664
	ds_read_b64_tr_b16 v[124:125], v231 offset:53248
	ds_read_b64_tr_b16 v[126:127], v232 offset:53760
	ds_read_b64_tr_b16 v[136:137], v231 offset:57344
	ds_read_b64_tr_b16 v[138:139], v232 offset:57856
	ds_read_b64_tr_b16 v[140:141], v231 offset:61440
	ds_read_b64_tr_b16 v[142:143], v232 offset:61952
	s_waitcnt lgkmcnt(14)
	v_mfma_f32_16x16x32_bf16 v[52:55], v[156:159], v[72:75], v[52:55]
	s_add_u32 s40, s40, 0xfff00000
	s_addc_u32 s41, s41, -1
	s_add_i32 s59, s59, 1
	s_waitcnt lgkmcnt(12)
	v_mfma_f32_16x16x32_bf16 v[52:55], v[194:197], v[80:83], v[52:55]
	s_add_i32 s38, s38, -1
	s_waitcnt lgkmcnt(10)
; #define GAS __attribute__((address_space(1)))
; __device__ __forceinline__ unsigned cvt_pk_bf16(float lo, float hi) { unsigned r; asm volatile("v_cvt_pk_bf16_f32 %0, %1, %2" : "=v"(r) : "v"(lo), "v"(hi)); return r; }
; __device__ __forceinline__ bf16x8 pack8(s16x4 lo, s16x4 hi) { return (bf16x8){lo[0], lo[1], lo[2], lo[3], hi[0], hi[1], hi[2], hi[3]}; }
; #define SCAN_BAR() asm volatile("s_waitcnt lgkmcnt(0)\n\ts_barrier" ::: "memory")
; #define SCAN_KREAD(b_, mt_) do { _Pragma("unroll") for (int ks = 0; ks < 4; ++ks) { const int ko = ((p & 1) ? LK1 : LK0) + 32 * ks * QS; kl[b_][ks] = tr_read(bKlo[mt_] + ko); kh[b_][ks] = tr_read(bKhi[mt_] + ko); } } while (0)
; __device__ __forceinline__ void scan_phase(const Frame& F, const bf16_t* Q, const bf16_t* K, const bf16_t* V, const bf16_t* PB, bf16_t* OF, bf16_t* OB, int half) {
;     ...
;                 for (int mt = 0; mt < 4; ++mt) { if (mt < 3) SCAN_KREAD((mt + 1) & 1, mt + 1);
;                     f32x4 acc = Rt[4 * p + mt] * c1;
; #pragma unroll
;                     for (int ks = 0; ks < 4; ++ks) acc = __builtin_amdgcn_mfma_f32_16x16x32_bf16(pack8(kl[mt & 1][ks], kh[mt & 1][ks]), Vf[ks], acc, 0, 0, 0);
;                     Rt[4 * p + mt] = acc; }
;     ...
;                 __builtin_amdgcn_sched_group_barrier(0x100, 8, 0);
;                 __builtin_amdgcn_sched_group_barrier(0x100, 8, 0); __builtin_amdgcn_sched_group_barrier(0x8, 4, 0);
;                 __builtin_amdgcn_sched_group_barrier(0x100, 8, 0); __builtin_amdgcn_sched_group_barrier(0x8, 4, 0);
;                 __builtin_amdgcn_sched_group_barrier(0x100, 8, 0); __builtin_amdgcn_sched_group_barrier(0x8, 4, 0);
;                 __builtin_amdgcn_sched_group_barrier(0x8, 4, 0);
;                 }
;                 if (p == 3) {
;                     bf16_t* ob_ = O + r0 * 4096 + head * 512 + vq * 128; const unsigned lo_ = (unsigned)(l15_l * 4096 + 16 * wv + 4 * quad);
;                     float fi = __builtin_amdgcn_exp2f(lg2 * (float)(dir ? 128 - l15_l : l15_l + 1));
; #pragma unroll
;                     for (int it = 0; it < 8; ++it) {
;                         *(GAS u32x2*)(ob_ + (size_t)(16 * it) * 4096 + lo_) = (u32x2){cvt_pk_bf16(Ot[it][0] * fi, Ot[it][1] * fi), cvt_pk_bf16(Ot[it][2] * fi, Ot[it][3] * fi)}; fi *= gm16; }
;                 }
;                 SCAN_BAR();
	v_mfma_f32_16x16x32_bf16 v[52:55], v[224:227], v[88:91], v[52:55]
	s_waitcnt lgkmcnt(8)
	v_mfma_f32_16x16x32_bf16 v[52:55], v[234:237], v[92:95], v[52:55]
	ds_read_b64_tr_b16 v[156:157], v233 offset:49152
	ds_read_b64_tr_b16 v[158:159], v241 offset:49664
	ds_read_b64_tr_b16 v[194:195], v233 offset:53248
	ds_read_b64_tr_b16 v[196:197], v241 offset:53760
	ds_read_b64_tr_b16 v[224:225], v233 offset:57344
	ds_read_b64_tr_b16 v[226:227], v241 offset:57856
	ds_read_b64_tr_b16 v[228:229], v233 offset:61440
	ds_read_b64_tr_b16 v[230:231], v241 offset:61952
	s_waitcnt lgkmcnt(14)
	v_mfma_f32_16x16x32_bf16 v[56:59], v[120:123], v[72:75], v[56:59]
	s_waitcnt lgkmcnt(12)
	v_mfma_f32_16x16x32_bf16 v[56:59], v[124:127], v[80:83], v[56:59]
	s_waitcnt lgkmcnt(10)
	v_mfma_f32_16x16x32_bf16 v[56:59], v[136:139], v[88:91], v[56:59]
	s_waitcnt lgkmcnt(8)
	v_mfma_f32_16x16x32_bf16 v[56:59], v[140:143], v[92:95], v[56:59]
	s_waitcnt lgkmcnt(6)
	v_mfma_f32_16x16x32_bf16 v[60:63], v[156:159], v[72:75], v[60:63]
	v_mul_f32_e32 v72, s54, v238
	s_waitcnt lgkmcnt(4)
	v_mfma_f32_16x16x32_bf16 v[60:63], v[194:197], v[80:83], v[60:63]
	v_exp_f32_e32 v82, v72
	v_lshl_add_u64 v[72:73], v[192:193], 1, s[12:13]
	s_mov_b32 s12, 0x180000
	s_waitcnt lgkmcnt(2)
	v_mfma_f32_16x16x32_bf16 v[60:63], v[224:227], v[88:91], v[60:63]
	v_mul_f32_e32 v74, v82, v128
	v_mul_f32_e32 v75, v82, v129
	v_cvt_pk_bf16_f32 v74, v74, v75
	v_mul_f32_e32 v75, v82, v130
	v_mul_f32_e32 v80, v82, v131
	v_cvt_pk_bf16_f32 v75, v75, v80
	v_add_co_u32_e32 v80, vcc, s6, v72
	v_mul_f32_e32 v82, s87, v82
	s_nop 0
	v_addc_co_u32_e32 v81, vcc, 0, v73, vcc
	global_store_dwordx2 v[80:81], v[74:75], off
	v_mul_f32_e32 v74, v82, v132
	v_mul_f32_e32 v75, v82, v133
	v_cvt_pk_bf16_f32 v74, v74, v75
	v_mul_f32_e32 v75, v82, v134
	v_mul_f32_e32 v80, v82, v135
	v_cvt_pk_bf16_f32 v75, v75, v80
	v_add_co_u32_e32 v80, vcc, s7, v72
	v_mul_f32_e32 v82, s87, v82
	s_nop 0
	v_addc_co_u32_e32 v81, vcc, 0, v73, vcc
	global_store_dwordx2 v[80:81], v[74:75], off
	v_mul_f32_e32 v74, v82, v104
	v_mul_f32_e32 v75, v82, v105
	v_cvt_pk_bf16_f32 v74, v74, v75
	v_mul_f32_e32 v75, v82, v106
	v_mul_f32_e32 v80, v82, v107
	v_cvt_pk_bf16_f32 v75, v75, v80
	v_add_co_u32_e32 v80, vcc, s4, v72
	v_mul_f32_e32 v82, s87, v82
	s_nop 0
	v_addc_co_u32_e32 v81, vcc, 0, v73, vcc
	global_store_dwordx2 v[80:81], v[74:75], off
	v_mul_f32_e32 v74, v82, v108
	v_mul_f32_e32 v75, v82, v109
	v_cvt_pk_bf16_f32 v74, v74, v75
	v_mul_f32_e32 v75, v82, v110
	v_mul_f32_e32 v80, v82, v111
	v_cvt_pk_bf16_f32 v75, v75, v80
	v_add_co_u32_e32 v80, vcc, s5, v72
	v_mul_f32_e32 v82, s87, v82
	s_nop 0
	v_addc_co_u32_e32 v81, vcc, 0, v73, vcc
	global_store_dwordx2 v[80:81], v[74:75], off
	v_mul_f32_e32 v74, v82, v112
	v_mul_f32_e32 v75, v82, v113
	v_cvt_pk_bf16_f32 v74, v74, v75
	v_mul_f32_e32 v75, v82, v114
	v_mul_f32_e32 v80, v82, v115
	v_cvt_pk_bf16_f32 v75, v75, v80
	v_add_co_u32_e32 v80, vcc, s12, v72
	v_mul_f32_e32 v82, s87, v82
	s_nop 0
	v_addc_co_u32_e32 v81, vcc, 0, v73, vcc
	global_store_dwordx2 v[80:81], v[74:75], off
	v_mul_f32_e32 v74, v82, v100
	v_mul_f32_e32 v75, v82, v101
	v_cvt_pk_bf16_f32 v74, v74, v75
	v_mul_f32_e32 v75, v82, v102
	v_mul_f32_e32 v80, v82, v103
	s_mov_b32 s12, 0x1a0000
	v_cvt_pk_bf16_f32 v75, v75, v80
	v_add_co_u32_e32 v80, vcc, s12, v72
	v_mul_f32_e32 v82, s87, v82
	s_nop 0
	v_addc_co_u32_e32 v81, vcc, 0, v73, vcc
	global_store_dwordx2 v[80:81], v[74:75], off
	v_mul_f32_e32 v74, v82, v96
	v_mul_f32_e32 v75, v82, v97
	v_cvt_pk_bf16_f32 v74, v74, v75
	v_mul_f32_e32 v75, v82, v98
	v_mul_f32_e32 v80, v82, v99
	s_mov_b32 s12, 0x1c0000
	v_cvt_pk_bf16_f32 v75, v75, v80
	v_add_co_u32_e32 v80, vcc, s12, v72
	s_mov_b32 s12, 0x1e0000
	s_nop 0
	v_addc_co_u32_e32 v81, vcc, 0, v73, vcc
	global_store_dwordx2 v[80:81], v[74:75], off
	v_mul_f32_e32 v75, s87, v82
	v_mul_f32_e32 v74, v75, v116
	v_mul_f32_e32 v80, v75, v117
	v_add_co_u32_e32 v72, vcc, s12, v72
	v_cvt_pk_bf16_f32 v74, v74, v80
	v_mul_f32_e32 v80, v75, v118
	v_mul_f32_e32 v75, v75, v119
	v_addc_co_u32_e32 v73, vcc, 0, v73, vcc
	s_waitcnt lgkmcnt(0)
	v_mfma_f32_16x16x32_bf16 v[60:63], v[228:231], v[92:95], v[60:63]
	v_cvt_pk_bf16_f32 v75, v80, v75
	global_store_dwordx2 v[72:73], v[74:75], off
	s_add_i32 s12, s48, s40
	s_add_u32 s42, s42, 0xfff80000
	s_waitcnt lgkmcnt(0)
	s_barrier
	s_addc_u32 s43, s43, -1
	s_cmp_eq_u32 s12, 0xffe00000
	s_cbranch_scc1 .LBB0_984
	.p2align 6
; #define LAS __attribute__((address_space(3)))
; __device__ __forceinline__ s16x4 tr_read(LAS unsigned char* p) { return __builtin_bit_cast(s16x4, __builtin_amdgcn_ds_read_tr16_b64_v4i16((LAS v4i16_t*)p)); }
; __device__ __forceinline__ bf16x8 pack8(s16x4 lo, s16x4 hi) { return (bf16x8){lo[0], lo[1], lo[2], lo[3], hi[0], hi[1], hi[2], hi[3]}; }
; template <int M, int N, class Fn> __device__ __forceinline__ void mattn_sfor(Fn&& f) { if constexpr (M < N) { f(std::integral_constant<int, M>{}); mattn_sfor<M + 1, N>(f); } }
; __device__ __forceinline__ void scan_phase(const Frame& F, const bf16_t* Q, const bf16_t* K, const bf16_t* V, const bf16_t* PB, bf16_t* OF, bf16_t* OB, int half) {
;     ...
;             for (int p = 0; p < 4; ++p) {
;                 if (p < 3 || more) SCAN_WRITE_QK((p + 1) & 1);
;                 if (p == 1 && more) SCAN_DMA_VP(cn);
;                 if (p < 2) SCAN_LOAD_QK(c, p + 2); else if (more) SCAN_LOAD_QK(cn, p - 2);
;                 if (p == 0) {
; #pragma unroll
;                     for (int ks = 0; ks < 4; ++ks) { const s16x4 lo = tr_read(bVlo + 32 * ks * 256), hi = tr_read(bVhi + 32 * ks * 256); Vf[ks] = pack8(lo, hi); }
;                     __builtin_amdgcn_sched_barrier(0);
;                     { u32x4 pwb[2];
;                       { constexpr int q0_ = pv_pair(dir, 0); pwb[0] = *(const LAS u32x4*)(bPk[q0_ & 3] + 16 * (q0_ >> 2) * 256); }
;                       __builtin_amdgcn_sched_group_barrier(0x100, 1, 0);
;                       mattn_sfor<0, 20>([&](auto n_) { constexpr int n = decltype(n_)::value, pr = pv_pair(dir, n), it = pr >> 2, ks = pr & 3, dks = ks - (it >> 1);
;                           if constexpr (n + 1 < 20) { constexpr int nx = pv_pair(dir, n + 1); pwb[(n + 1) & 1] = *(const LAS u32x4*)(bPk[nx & 3] + 16 * (nx >> 2) * 256); }
;                           u32x4 pw = pwb[n & 1];
;                           if constexpr (dks == 0) { pw.x &= pmk[it & 1][0]; pw.y &= pmk[it & 1][1]; pw.z &= pmk[it & 1][2]; pw.w &= pmk[it & 1][3]; }
;                           Ot[it] = __builtin_amdgcn_mfma_f32_16x16x32_bf16(Vf[ks], __builtin_bit_cast(bf16x8, pw), Ot[it], 0, 0, 0);
;                           __builtin_amdgcn_sched_group_barrier(0x100, 1, 0); __builtin_amdgcn_sched_group_barrier(0x8, 1, 0); }); }
.LBB0_978:
	v_lshl_add_u64 v[158:159], v[154:155], 0, s[42:43]
	s_mov_b32 s12, 0x10780000
	v_add_co_u32_e32 v72, vcc, s12, v158
	v_mov_b32_e32 v192, v161
	v_mov_b32_e32 v74, v162
	v_lshl_add_u64 v[156:157], v[152:153], 0, s[42:43]
	v_addc_co_u32_e32 v73, vcc, 0, v159, vcc
	s_mov_b32 s12, 0x4a880000
	global_load_dwordx4 v[96:99], v[72:73], off offset:256
	v_add_co_u32_e32 v72, vcc, s12, v156
	s_mov_b32 s12, 0x107c0000
	s_nop 0
	v_addc_co_u32_e32 v73, vcc, 0, v157, vcc
	global_load_dwordx4 v[100:103], v[72:73], off offset:256
	v_add_co_u32_e32 v72, vcc, s12, v158
	s_mov_b32 s12, 0x4a8c0000
	s_nop 0
	v_addc_co_u32_e32 v73, vcc, 0, v159, vcc
	global_load_dwordx4 v[104:107], v[72:73], off offset:256
	v_add_co_u32_e32 v72, vcc, s12, v156
	s_waitcnt vmcnt(14)
	ds_write_b128 v214, v[64:67] offset:16384
	v_addc_co_u32_e32 v73, vcc, 0, v157, vcc
	global_load_dwordx4 v[108:111], v[72:73], off offset:256
	s_waitcnt vmcnt(14)
	ds_write_b128 v214, v[68:71] offset:49152
	s_waitcnt vmcnt(13)
	ds_write_b128 v214, v[76:79] offset:24576
	s_waitcnt vmcnt(12)
	ds_write_b128 v214, v[84:87] offset:57344
	v_add_u32_e32 v64, v175, v168
	v_add_u32_e32 v65, v169, v168
	v_lshlrev_b32_e32 v112, 3, v74
	ds_read_b64_tr_b16 v[72:73], v64
	ds_read_b64_tr_b16 v[80:81], v64 offset:8192
	ds_read_b64_tr_b16 v[88:89], v64 offset:16384
	ds_read_b64_tr_b16 v[92:93], v64 offset:24576
	ds_read_b64_tr_b16 v[74:75], v65 offset:1024
	ds_read_b64_tr_b16 v[82:83], v65 offset:9216
	ds_read_b64_tr_b16 v[90:91], v65 offset:17408
	ds_read_b64_tr_b16 v[94:95], v65 offset:25600
	v_cvt_f32_i32_e32 v124, v112
	s_cmp_lt_u32 s59, s73
	s_cselect_b64 s[44:45], -1, 0
	s_cmp_ge_u32 s59, s73
	v_add_u32_e32 v84, v170, v171
	ds_read_b128 v[64:67], v84
	v_add_u32_e32 v116, v170, v172
	ds_read_b128 v[68:71], v116
	v_add_u32_e32 v120, v170, v173
	v_add_u32_e32 v125, v170, v174
	s_waitcnt lgkmcnt(1)
	v_and_b32_e32 v64, v64, v191
	v_and_b32_e32 v65, v65, v198
	v_and_b32_e32 v66, v66, v199
	v_and_b32_e32 v67, v67, v200
	s_nop 1
	v_mfma_f32_16x16x32_bf16 v[64:67], v[72:75], v[64:67], 0
	ds_read_b128 v[76:79], v120
	s_waitcnt lgkmcnt(1)
	v_mfma_f32_16x16x32_bf16 v[64:67], v[80:83], v[68:71], v[64:67]
	ds_read_b128 v[68:71], v125
	s_waitcnt lgkmcnt(1)
	v_mfma_f32_16x16x32_bf16 v[64:67], v[88:91], v[76:79], v[64:67]
	ds_read_b128 v[76:79], v84 offset:4096
	s_waitcnt lgkmcnt(0)
	v_and_b32_e32 v76, v76, v201
	v_mfma_f32_16x16x32_bf16 v[64:67], v[92:95], v[68:71], v[64:67]
	ds_read_b128 v[68:71], v116 offset:4096
	v_and_b32_e32 v77, v77, v202
	v_and_b32_e32 v78, v78, v203
	v_and_b32_e32 v79, v79, v204
	s_nop 1
	v_mfma_f32_16x16x32_bf16 v[76:79], v[72:75], v[76:79], 0
	ds_read_b128 v[84:87], v120 offset:4096
	s_waitcnt lgkmcnt(1)
	v_mfma_f32_16x16x32_bf16 v[68:71], v[80:83], v[68:71], v[76:79]
	s_nop 4
	ds_read_b128 v[76:79], v125 offset:4096
	s_waitcnt lgkmcnt(1)
	v_mfma_f32_16x16x32_bf16 v[68:71], v[88:91], v[84:87], v[68:71]
	ds_read_b128 v[84:87], v116 offset:8192
	s_waitcnt lgkmcnt(0)
	v_and_b32_e32 v84, v84, v191
	v_mfma_f32_16x16x32_bf16 v[68:71], v[92:95], v[76:79], v[68:71]
	ds_read_b128 v[76:79], v120 offset:8192
	v_and_b32_e32 v85, v85, v198
	v_and_b32_e32 v86, v86, v199
	v_and_b32_e32 v87, v87, v200
	s_nop 1
	v_mfma_f32_16x16x32_bf16 v[84:87], v[80:83], v[84:87], 0
	ds_read_b128 v[112:115], v125 offset:8192
	s_waitcnt lgkmcnt(1)
	v_mfma_f32_16x16x32_bf16 v[76:79], v[88:91], v[76:79], v[84:87]
	s_nop 4
	ds_read_b128 v[84:87], v116 offset:12288
	s_waitcnt lgkmcnt(1)
	v_mfma_f32_16x16x32_bf16 v[76:79], v[92:95], v[112:115], v[76:79]
	ds_read_b128 v[112:115], v120 offset:12288
	s_waitcnt lgkmcnt(1)
	v_and_b32_e32 v84, v84, v201
	v_and_b32_e32 v85, v85, v202
	v_and_b32_e32 v86, v86, v203
	v_and_b32_e32 v87, v87, v204
	s_nop 1
	v_mfma_f32_16x16x32_bf16 v[84:87], v[80:83], v[84:87], 0
	ds_read_b128 v[116:119], v125 offset:12288
	s_waitcnt lgkmcnt(1)
	v_mfma_f32_16x16x32_bf16 v[84:87], v[88:91], v[112:115], v[84:87]
	ds_read_b128 v[112:115], v120 offset:16384
	s_waitcnt lgkmcnt(0)
	v_and_b32_e32 v112, v112, v191
	v_and_b32_e32 v113, v113, v198
	v_and_b32_e32 v114, v114, v199
	v_and_b32_e32 v115, v115, v200
	v_mfma_f32_16x16x32_bf16 v[84:87], v[92:95], v[116:119], v[84:87]
	ds_read_b128 v[116:119], v125 offset:16384
	v_mfma_f32_16x16x32_bf16 v[112:115], v[88:91], v[112:115], 0
	ds_read_b128 v[120:123], v120 offset:20480
	s_waitcnt lgkmcnt(1)
	v_mfma_f32_16x16x32_bf16 v[128:131], v[92:95], v[116:119], v[112:115]
	s_waitcnt lgkmcnt(0)
	v_and_b32_e32 v116, v120, v201
	v_and_b32_e32 v117, v121, v202
	s_nop 1
	ds_read_b128 v[112:115], v125 offset:20480
	v_and_b32_e32 v118, v122, v203
	v_and_b32_e32 v119, v123, v204
	s_nop 1
	v_mfma_f32_16x16x32_bf16 v[116:119], v[88:91], v[116:119], 0
	ds_read_b128 v[120:123], v125 offset:24576
	s_waitcnt lgkmcnt(1)
	v_mfma_f32_16x16x32_bf16 v[132:135], v[92:95], v[112:115], v[116:119]
	ds_read_b128 v[112:115], v125 offset:28672
	s_waitcnt lgkmcnt(0)
; __device__ __forceinline__ unsigned cvt_pk_bf16(float lo, float hi) { unsigned r; asm volatile("v_cvt_pk_bf16_f32 %0, %1, %2" : "=v"(r) : "v"(lo), "v"(hi)); return r; }
; __device__ __forceinline__ float bf_lo(unsigned w) { return __uint_as_float(w << 16); }
; __device__ __forceinline__ float bf_hi(unsigned w) { return __uint_as_float(w & 0xffff0000u); }
; #define SCAN_QREAD(b_, it_) do { _Pragma("unroll") for (int ks = 0; ks < 2; ++ks) { const int qo = ((p & 1) ? LQ1 : LQ0) + 16 * (it_) * QS; \
;                         const u32x2 lo = *(const volatile LAS u32x2*)(bQs[ks][0] + qo), hi = *(const volatile LAS u32x2*)(bQs[ks][1] + qo);     qf[b_][ks] = (u32x4){lo.x, lo.y, hi.x, hi.y}; } } while (0)
; __device__ __forceinline__ void scan_phase(const Frame& F, const bf16_t* Q, const bf16_t* K, const bf16_t* V, const bf16_t* PB, bf16_t* OF, bf16_t* OB, int half) {
;     ...
;                     { float fk = __builtin_amdgcn_exp2f(lg2 * (float)(dir ? 8 * quad_l : 127 - 8 * quad_l));
; #pragma unroll
;                       for (int ks = 0; ks < 4; ++ks) { u32x4 vw = __builtin_bit_cast(u32x4, Vf[ks]); float f = fk;
; #pragma unroll
;                         for (int e2 = 0; e2 < 4; ++e2) { const float f0 = f, f1 = f * gm1; f = f1 * gm1;
;                             vw[e2] = cvt_pk_bf16(bf_lo(vw[e2]) * f0, bf_hi(vw[e2]) * f1); }
;                         Vf[ks] = __builtin_bit_cast(bf16x8, vw); fk *= gm32; } }
;                 }
;                 __builtin_amdgcn_sched_barrier(0);
;                 {
;                     bf16x8 Rf[2];
; #pragma unroll
;                     for (int ks = 0; ks < 2; ++ks) { const f32x4 r0v = Rt[4 * p + 2 * ks], r1v = Rt[4 * p + 2 * ks + 1];
;                         const u32x4 wvv = {cvt_pk_bf16(r0v[0], r0v[1]), cvt_pk_bf16(r0v[2], r0v[3]), cvt_pk_bf16(r1v[0], r1v[1]), cvt_pk_bf16(r1v[2], r1v[3])};
;                         Rf[ks] = __builtin_bit_cast(bf16x8, wvv); }
;                     u32x4 qf[2][2];
;     ...
;                     SCAN_QREAD(0, 0);
; #pragma unroll
;                     for (int it = 0; it < 8; ++it) { if (it < 7) SCAN_QREAD((it + 1) & 1, it + 1);
; #pragma unroll
;                         for (int ks = 0; ks < 2; ++ks) Ot[it] = __builtin_amdgcn_mfma_f32_16x16x32_bf16(Rf[ks], __builtin_bit_cast(bf16x8, qf[it & 1][ks]), Ot[it], 0, 0, 0); }
	v_and_b32_e32 v112, v112, v201
	s_nop 1
	v_and_b32_e32 v116, v120, v191
	v_and_b32_e32 v117, v121, v198
	v_and_b32_e32 v118, v122, v199
	v_and_b32_e32 v119, v123, v200
	v_and_b32_e32 v113, v113, v202
	v_and_b32_e32 v114, v114, v203
	v_and_b32_e32 v115, v115, v204
	v_mfma_f32_16x16x32_bf16 v[136:139], v[92:95], v[116:119], 0
	s_nop 0
	v_mfma_f32_16x16x32_bf16 v[140:143], v[92:95], v[112:115], 0
	v_mul_f32_e32 v112, s54, v124
	v_exp_f32_e32 v112, v112
	v_lshlrev_b32_e32 v113, 16, v72
	v_and_b32_e32 v72, 0xffff0000, v72
	v_lshlrev_b32_e32 v116, 16, v73
	v_mul_f32_e32 v114, s85, v112
	v_mul_f32_e32 v113, v112, v113
	v_mul_f32_e32 v115, s85, v114
	v_mul_f32_e32 v72, v114, v72
	v_cvt_pk_bf16_f32 v72, v113, v72
	v_mul_f32_e32 v113, s85, v115
	v_mul_f32_e32 v114, s85, v113
	v_and_b32_e32 v73, 0xffff0000, v73
	v_mul_f32_e32 v115, v115, v116
	v_mul_f32_e32 v73, v113, v73
	v_mul_f32_e32 v113, s85, v114
	v_lshlrev_b32_e32 v116, 16, v74
	v_and_b32_e32 v74, 0xffff0000, v74
	v_cvt_pk_bf16_f32 v73, v115, v73
	v_mul_f32_e32 v115, s85, v113
	v_mul_f32_e32 v114, v114, v116
	v_mul_f32_e32 v74, v113, v74
	v_cvt_pk_bf16_f32 v74, v114, v74
	v_mul_f32_e32 v113, s85, v115
	v_lshlrev_b32_e32 v114, 16, v75
	v_and_b32_e32 v75, 0xffff0000, v75
	v_mul_f32_e32 v112, s86, v112
	v_mul_f32_e32 v114, v115, v114
	v_mul_f32_e32 v75, v113, v75
	v_mul_f32_e32 v113, s85, v112
	v_cvt_pk_bf16_f32 v75, v114, v75
	v_mul_f32_e32 v114, s85, v113
	v_lshlrev_b32_e32 v115, 16, v80
	v_and_b32_e32 v80, 0xffff0000, v80
	v_mul_f32_e32 v115, v112, v115
	v_mul_f32_e32 v80, v113, v80
	v_mul_f32_e32 v113, s85, v114
	v_cvt_pk_bf16_f32 v80, v115, v80
	v_mul_f32_e32 v115, s85, v113
	v_lshlrev_b32_e32 v116, 16, v81
	v_and_b32_e32 v81, 0xffff0000, v81
	v_mul_f32_e32 v114, v114, v116
	v_mul_f32_e32 v81, v113, v81
	v_mul_f32_e32 v113, s85, v115
	v_lshlrev_b32_e32 v116, 16, v82
	v_and_b32_e32 v82, 0xffff0000, v82
	v_cvt_pk_bf16_f32 v81, v114, v81
	v_mul_f32_e32 v114, s85, v113
	v_mul_f32_e32 v115, v115, v116
	v_mul_f32_e32 v82, v113, v82
	v_cvt_pk_bf16_f32 v82, v115, v82
	v_mul_f32_e32 v113, s85, v114
	v_lshlrev_b32_e32 v115, 16, v83
	v_and_b32_e32 v83, 0xffff0000, v83
	v_mul_f32_e32 v112, s86, v112
	v_mul_f32_e32 v114, v114, v115
	v_mul_f32_e32 v83, v113, v83
	v_mul_f32_e32 v113, s85, v112
	v_cvt_pk_bf16_f32 v83, v114, v83
	v_mul_f32_e32 v114, s85, v113
	v_lshlrev_b32_e32 v115, 16, v88
	v_and_b32_e32 v88, 0xffff0000, v88
	v_mul_f32_e32 v115, v112, v115
	v_mul_f32_e32 v88, v113, v88
	v_mul_f32_e32 v113, s85, v114
	v_cvt_pk_bf16_f32 v88, v115, v88
	v_mul_f32_e32 v115, s85, v113
	v_lshlrev_b32_e32 v116, 16, v89
	v_and_b32_e32 v89, 0xffff0000, v89
	v_mul_f32_e32 v114, v114, v116
	v_mul_f32_e32 v89, v113, v89
	v_mul_f32_e32 v113, s85, v115
	v_lshlrev_b32_e32 v116, 16, v90
	v_and_b32_e32 v90, 0xffff0000, v90
	v_cvt_pk_bf16_f32 v89, v114, v89
	v_mul_f32_e32 v114, s85, v113
	v_mul_f32_e32 v115, v115, v116
	v_mul_f32_e32 v90, v113, v90
	v_cvt_pk_bf16_f32 v90, v115, v90
	v_mul_f32_e32 v113, s85, v114
	v_lshlrev_b32_e32 v115, 16, v91
	v_and_b32_e32 v91, 0xffff0000, v91
	v_mul_f32_e32 v112, s86, v112
	v_mul_f32_e32 v114, v114, v115
	v_mul_f32_e32 v91, v113, v91
	v_mul_f32_e32 v113, s85, v112
	v_lshlrev_b32_e32 v115, 16, v92
	v_and_b32_e32 v92, 0xffff0000, v92
	v_cvt_pk_bf16_f32 v91, v114, v91
	v_mul_f32_e32 v114, s85, v113
	v_mul_f32_e32 v112, v112, v115
	v_mul_f32_e32 v92, v113, v92
	v_cvt_pk_bf16_f32 v92, v112, v92
	v_mul_f32_e32 v112, s85, v114
	v_mul_f32_e32 v113, s85, v112
	v_lshlrev_b32_e32 v115, 16, v93
	v_and_b32_e32 v93, 0xffff0000, v93
	v_mul_f32_e32 v114, v114, v115
	v_mul_f32_e32 v93, v112, v93
	v_mul_f32_e32 v112, s85, v113
	v_lshlrev_b32_e32 v115, 16, v94
	v_and_b32_e32 v94, 0xffff0000, v94
	v_cvt_pk_bf16_f32 v93, v114, v93
	v_mul_f32_e32 v114, s85, v112
	v_mul_f32_e32 v113, v113, v115
	v_mul_f32_e32 v94, v112, v94
	v_cvt_pk_bf16_f32 v94, v113, v94
	v_mul_f32_e32 v112, s85, v114
	v_lshlrev_b32_e32 v113, 16, v95
	v_and_b32_e32 v95, 0xffff0000, v95
	v_mul_f32_e32 v113, v114, v113
	v_mul_f32_e32 v95, v112, v95
	v_cvt_pk_bf16_f32 v95, v113, v95
	v_add_u32_e32 v223, v163, v164
	v_add_u32_e32 v224, v163, v165
	v_cvt_pk_bf16_f32 v228, v44, v45
	v_cvt_pk_bf16_f32 v229, v46, v47
	v_cvt_pk_bf16_f32 v230, v40, v41
	v_cvt_pk_bf16_f32 v231, v42, v43
	v_cvt_pk_bf16_f32 v242, v36, v37
	v_cvt_pk_bf16_f32 v243, v38, v39
	v_cvt_pk_bf16_f32 v244, v32, v33
	v_cvt_pk_bf16_f32 v245, v34, v35
	ds_read_b64 v[112:113], v223
	ds_read_b64 v[114:115], v224
	v_add_u32_e32 v225, v163, v166
	v_add_u32_e32 v226, v163, v167
	ds_read_b64 v[116:117], v225
	ds_read_b64 v[118:119], v226
	ds_read_b64 v[120:121], v223 offset:2048
	ds_read_b64 v[122:123], v224 offset:2048
	ds_read_b64 v[124:125], v225 offset:2048
	ds_read_b64 v[126:127], v226 offset:2048
	s_waitcnt lgkmcnt(6)
	v_mfma_f32_16x16x32_bf16 v[64:67], v[228:231], v[112:115], v[64:67]
	s_waitcnt lgkmcnt(4)
	v_mfma_f32_16x16x32_bf16 v[112:115], v[242:245], v[116:119], v[64:67]
	s_nop 5
	ds_read_b64 v[64:65], v223 offset:4096
	ds_read_b64 v[66:67], v224 offset:4096
	ds_read_b64 v[246:247], v225 offset:4096
	ds_read_b64 v[248:249], v226 offset:4096
	s_waitcnt lgkmcnt(6)
	v_mfma_f32_16x16x32_bf16 v[68:71], v[228:231], v[120:123], v[68:71]
	s_waitcnt lgkmcnt(4)
	v_mfma_f32_16x16x32_bf16 v[116:119], v[242:245], v[124:127], v[68:71]
	s_nop 5
	ds_read_b64 v[68:69], v223 offset:6144
	ds_read_b64 v[70:71], v224 offset:6144
	ds_read_b64 v[124:125], v225 offset:6144
	ds_read_b64 v[126:127], v226 offset:6144
	s_waitcnt lgkmcnt(6)
	v_mfma_f32_16x16x32_bf16 v[64:67], v[228:231], v[64:67], v[76:79]
	s_waitcnt lgkmcnt(4)
; __device__ __forceinline__ void scan_phase(const Frame& F, const bf16_t* Q, const bf16_t* K, const bf16_t* V, const bf16_t* PB, bf16_t* OF, bf16_t* OB, int half) {
;     ...
;                     for (int ks = 0; ks < 2; ++ks) { const f32x4 r0v = Rt[4 * p + 2 * ks], r1v = Rt[4 * p + 2 * ks + 1];
;                         const u32x4 wvv = {cvt_pk_bf16(r0v[0], r0v[1]), cvt_pk_bf16(r0v[2], r0v[3]), cvt_pk_bf16(r1v[0], r1v[1]), cvt_pk_bf16(r1v[2], r1v[3])};
;                         Rf[ks] = __builtin_bit_cast(bf16x8, wvv); }
;                     u32x4 qf[2][2];
;     ...
;                     SCAN_QREAD(0, 0);
; #pragma unroll
;                     for (int it = 0; it < 8; ++it) { if (it < 7) SCAN_QREAD((it + 1) & 1, it + 1);
; #pragma unroll
;                         for (int ks = 0; ks < 2; ++ks) Ot[it] = __builtin_amdgcn_mfma_f32_16x16x32_bf16(Rf[ks], __builtin_bit_cast(bf16x8, qf[it & 1][ks]), Ot[it], 0, 0, 0); }
;     ...
;                     __builtin_amdgcn_sched_group_barrier(0x100, 4, 0);
;                     __builtin_amdgcn_sched_group_barrier(0x100, 4, 0); __builtin_amdgcn_sched_group_barrier(0x8, 2, 0);
;                     __builtin_amdgcn_sched_group_barrier(0x100, 4, 0); __builtin_amdgcn_sched_group_barrier(0x8, 2, 0);
;                     __builtin_amdgcn_sched_group_barrier(0x100, 4, 0); __builtin_amdgcn_sched_group_barrier(0x8, 2, 0);
;                     __builtin_amdgcn_sched_group_barrier(0x100, 4, 0); __builtin_amdgcn_sched_group_barrier(0x8, 2, 0);
;                     __builtin_amdgcn_sched_group_barrier(0x100, 4, 0); __builtin_amdgcn_sched_group_barrier(0x8, 2, 0);
;                     __builtin_amdgcn_sched_group_barrier(0x100, 4, 0); __builtin_amdgcn_sched_group_barrier(0x8, 2, 0);
;                     __builtin_amdgcn_sched_group_barrier(0x100, 4, 0); __builtin_amdgcn_sched_group_barrier(0x8, 2, 0);
;                     __builtin_amdgcn_sched_group_barrier(0x8, 2, 0);
;                 }
;                 __builtin_amdgcn_sched_barrier(0);
;                 { s16x4 kl[2][4], kh[2][4];
;     ...
;                 SCAN_KREAD(0, 0);
; #pragma unroll
;                 for (int mt = 0; mt < 4; ++mt) { if (mt < 3) SCAN_KREAD((mt + 1) & 1, mt + 1);
;                     f32x4 acc = Rt[4 * p + mt] * c1;
; #pragma unroll
	v_mfma_f32_16x16x32_bf16 v[120:123], v[242:245], v[246:249], v[64:67]
	s_nop 5
	ds_read_b64 v[64:65], v223 offset:8192
	ds_read_b64 v[66:67], v224 offset:8192
	ds_read_b64 v[76:77], v225 offset:8192
	ds_read_b64 v[78:79], v226 offset:8192
	s_waitcnt lgkmcnt(6)
	v_mfma_f32_16x16x32_bf16 v[68:71], v[228:231], v[68:71], v[84:87]
	s_waitcnt lgkmcnt(4)
	v_mfma_f32_16x16x32_bf16 v[124:127], v[242:245], v[124:127], v[68:71]
	s_nop 5
	ds_read_b64 v[68:69], v223 offset:10240
	ds_read_b64 v[70:71], v224 offset:10240
	ds_read_b64 v[84:85], v225 offset:10240
	ds_read_b64 v[86:87], v226 offset:10240
	s_waitcnt lgkmcnt(6)
	v_mfma_f32_16x16x32_bf16 v[64:67], v[228:231], v[64:67], v[128:131]
	s_waitcnt lgkmcnt(4)
	v_mfma_f32_16x16x32_bf16 v[128:131], v[242:245], v[76:79], v[64:67]
	s_nop 5
	ds_read_b64 v[64:65], v223 offset:12288
	ds_read_b64 v[66:67], v224 offset:12288
	ds_read_b64 v[76:77], v225 offset:12288
	ds_read_b64 v[78:79], v226 offset:12288
	s_waitcnt lgkmcnt(6)
	v_mfma_f32_16x16x32_bf16 v[68:71], v[228:231], v[68:71], v[132:135]
	s_waitcnt lgkmcnt(4)
	v_mfma_f32_16x16x32_bf16 v[132:135], v[242:245], v[84:87], v[68:71]
	s_nop 5
	ds_read_b64 v[68:69], v223 offset:14336
	ds_read_b64 v[70:71], v224 offset:14336
	ds_read_b64 v[84:85], v225 offset:14336
	ds_read_b64 v[86:87], v226 offset:14336
	s_waitcnt lgkmcnt(6)
	v_mfma_f32_16x16x32_bf16 v[64:67], v[228:231], v[64:67], v[136:139]
	s_waitcnt lgkmcnt(4)
	v_mfma_f32_16x16x32_bf16 v[136:139], v[242:245], v[76:79], v[64:67]
	s_waitcnt lgkmcnt(2)
	v_mfma_f32_16x16x32_bf16 v[64:67], v[228:231], v[68:71], v[140:143]
	s_waitcnt lgkmcnt(0)
	v_mfma_f32_16x16x32_bf16 v[140:143], v[242:245], v[84:87], v[64:67]
	v_add_u32_e32 v227, v182, v189
	v_add_u32_e32 v228, v182, v190
	s_nop 3
	ds_read_b64_tr_b16 v[64:65], v227 offset:32768
	ds_read_b64_tr_b16 v[66:67], v228 offset:33280
	ds_read_b64_tr_b16 v[68:69], v227 offset:36864
	ds_read_b64_tr_b16 v[70:71], v228 offset:37376
	v_mov_b32_e32 v145, v144
	ds_read_b64_tr_b16 v[76:77], v227 offset:40960
	ds_read_b64_tr_b16 v[78:79], v228 offset:41472
	v_add_u32_e32 v229, v182, v187
	v_add_u32_e32 v230, v182, v188
	v_mul_f32_e32 v46, v144, v46
	v_mul_f32_e32 v47, v145, v47
	v_mul_f32_e32 v44, v146, v44
	v_mul_f32_e32 v45, v147, v45
	ds_read_b64_tr_b16 v[84:85], v227 offset:45056
	ds_read_b64_tr_b16 v[86:87], v228 offset:45568
	ds_read_b64_tr_b16 v[242:243], v229 offset:32768
	ds_read_b64_tr_b16 v[244:245], v230 offset:33280
	ds_read_b64_tr_b16 v[246:247], v229 offset:36864
	ds_read_b64_tr_b16 v[248:249], v230 offset:37376
	ds_read_b64_tr_b16 v[194:195], v229 offset:40960
	ds_read_b64_tr_b16 v[196:197], v230 offset:41472
	ds_read_b64_tr_b16 v[238:239], v229 offset:45056
	ds_read_b64_tr_b16 v[240:241], v230 offset:45568
	s_waitcnt lgkmcnt(14)
	v_mfma_f32_16x16x32_bf16 v[44:47], v[64:67], v[72:75], v[44:47]
	v_add_u32_e32 v231, v182, v185
	v_add_u32_e32 v232, v182, v186
	v_mul_f32_e32 v42, v144, v42
	v_mul_f32_e32 v43, v145, v43
	s_waitcnt lgkmcnt(12)
	v_mfma_f32_16x16x32_bf16 v[44:47], v[68:71], v[80:83], v[44:47]
	v_mul_f32_e32 v40, v146, v40
	v_mul_f32_e32 v41, v147, v41
	v_add_u32_e32 v233, v182, v183
	v_mul_f32_e32 v38, v144, v38
	v_mul_f32_e32 v39, v145, v39
	s_waitcnt lgkmcnt(10)
	v_mfma_f32_16x16x32_bf16 v[44:47], v[76:79], v[88:91], v[44:47]
	v_mul_f32_e32 v36, v146, v36
	v_mul_f32_e32 v37, v147, v37
	v_mul_f32_e32 v34, v144, v34
	v_mul_f32_e32 v35, v145, v35
	v_mul_f32_e32 v32, v146, v32
	v_mul_f32_e32 v33, v147, v33
	s_waitcnt lgkmcnt(8)
	v_mfma_f32_16x16x32_bf16 v[44:47], v[84:87], v[92:95], v[44:47]
	ds_read_b64_tr_b16 v[64:65], v231 offset:32768
	ds_read_b64_tr_b16 v[66:67], v232 offset:33280
	ds_read_b64_tr_b16 v[68:69], v231 offset:36864
	ds_read_b64_tr_b16 v[70:71], v232 offset:37376
	ds_read_b64_tr_b16 v[76:77], v231 offset:40960
	ds_read_b64_tr_b16 v[78:79], v232 offset:41472
	ds_read_b64_tr_b16 v[84:85], v231 offset:45056
	ds_read_b64_tr_b16 v[86:87], v232 offset:45568
	s_waitcnt lgkmcnt(14)
	v_mfma_f32_16x16x32_bf16 v[40:43], v[242:245], v[72:75], v[40:43]
	s_waitcnt lgkmcnt(12)
	v_mfma_f32_16x16x32_bf16 v[40:43], v[246:249], v[80:83], v[40:43]
	s_waitcnt lgkmcnt(10)
	v_mfma_f32_16x16x32_bf16 v[40:43], v[194:197], v[88:91], v[40:43]
	s_waitcnt lgkmcnt(8)
	v_mfma_f32_16x16x32_bf16 v[40:43], v[238:241], v[92:95], v[40:43]
	v_add_u32_e32 v241, v182, v184
	ds_read_b64_tr_b16 v[194:195], v233 offset:32768
	ds_read_b64_tr_b16 v[196:197], v241 offset:33280
	ds_read_b64_tr_b16 v[242:243], v233 offset:36864
	ds_read_b64_tr_b16 v[244:245], v241 offset:37376
	ds_read_b64_tr_b16 v[246:247], v233 offset:40960
	ds_read_b64_tr_b16 v[248:249], v241 offset:41472
	ds_read_b64_tr_b16 v[234:235], v233 offset:45056
	ds_read_b64_tr_b16 v[236:237], v241 offset:45568
	s_waitcnt lgkmcnt(14)
	v_mfma_f32_16x16x32_bf16 v[36:39], v[64:67], v[72:75], v[36:39]
	s_waitcnt lgkmcnt(0)
	s_barrier
	s_waitcnt vmcnt(3)
	ds_write_b128 v214, v[96:99]
	s_waitcnt vmcnt(2)
	ds_write_b128 v214, v[100:103] offset:32768
	s_waitcnt lgkmcnt(14)
	v_mfma_f32_16x16x32_bf16 v[36:39], v[68:71], v[80:83], v[36:39]
	s_waitcnt vmcnt(1)
	ds_write_b128 v214, v[104:107] offset:8192
	s_waitcnt vmcnt(0)
	ds_write_b128 v214, v[108:111] offset:40960
	s_waitcnt lgkmcnt(14)
	v_mfma_f32_16x16x32_bf16 v[36:39], v[76:79], v[88:91], v[36:39]
	s_waitcnt lgkmcnt(12)
	v_mfma_f32_16x16x32_bf16 v[36:39], v[84:87], v[92:95], v[36:39]
	s_waitcnt lgkmcnt(10)
	v_mfma_f32_16x16x32_bf16 v[32:35], v[194:197], v[72:75], v[32:35]
	s_waitcnt lgkmcnt(8)
	v_mfma_f32_16x16x32_bf16 v[32:35], v[242:245], v[80:83], v[32:35]
	s_waitcnt lgkmcnt(6)
	v_mfma_f32_16x16x32_bf16 v[32:35], v[246:249], v[88:91], v[32:35]
	s_waitcnt lgkmcnt(4)
	v_mfma_f32_16x16x32_bf16 v[32:35], v[234:237], v[92:95], v[32:35]
	v_add_co_u32_e32 v64, vcc, 0x10780000, v158
	s_nop 1
	v_addc_co_u32_e32 v65, vcc, 0, v159, vcc
	v_add_co_u32_e32 v68, vcc, 0x4a880000, v156
	global_load_dwordx4 v[64:67], v[64:65], off offset:384
	s_nop 0
	v_addc_co_u32_e32 v69, vcc, 0, v157, vcc
	v_add_co_u32_e32 v76, vcc, 0x107c0000, v158
	global_load_dwordx4 v[68:71], v[68:69], off offset:384
	s_nop 0
	v_addc_co_u32_e32 v77, vcc, 0, v159, vcc
	v_add_co_u32_e32 v84, vcc, 0x4a8c0000, v156
	global_load_dwordx4 v[76:79], v[76:77], off offset:384
	s_nop 0
	v_addc_co_u32_e32 v85, vcc, 0, v157, vcc
	global_load_dwordx4 v[84:87], v[84:85], off offset:384
	s_cbranch_scc1 .LBB0_980
	s_add_u32 s12, s90, s40
	s_addc_u32 s13, s91, s41
	s_ashr_i32 s39, s38, 31
	s_lshl_b64 s[34:35], s[38:39], 18
	s_add_u32 s34, s88, s34
	s_mov_b32 s39, m0
	s_mov_b32 m0, s74
	s_nop 0
	global_load_lds_dwordx4 v215, s[12:13]
	s_mov_b32 m0, s39
	s_addc_u32 s35, s89, s35
	s_mov_b32 s39, m0
	s_mov_b32 m0, s75
	s_nop 0
	global_load_lds_dwordx4 v216, s[34:35]
	s_mov_b32 m0, s39
	s_nop 0
	s_mov_b32 s39, m0
	s_mov_b32 m0, s79
	s_nop 0
	global_load_lds_dwordx4 v217, s[12:13]
	s_mov_b32 m0, s39
	s_nop 0
	s_mov_b32 s39, m0
	s_mov_b32 m0, s80
	s_nop 0
	global_load_lds_dwordx4 v218, s[34:35]
	s_mov_b32 m0, s39
	s_nop 0
	s_mov_b32 s39, m0
	s_mov_b32 m0, s81
	s_nop 0
	global_load_lds_dwordx4 v219, s[12:13]
	s_mov_b32 m0, s39
	s_nop 0
	s_mov_b32 s39, m0
	s_mov_b32 m0, s82
	s_nop 0
	global_load_lds_dwordx4 v220, s[34:35]
	s_mov_b32 m0, s39
	s_nop 0
	s_mov_b32 s39, m0
	s_mov_b32 m0, s83
	s_nop 0
	global_load_lds_dwordx4 v221, s[12:13]
	s_mov_b32 m0, s39
	s_mov_b32 s12, m0
	s_mov_b32 m0, s84
	s_nop 0
	global_load_lds_dwordx4 v222, s[34:35]
	s_mov_b32 m0, s12
; __device__ __forceinline__ void scan_phase(const Frame& F, const bf16_t* Q, const bf16_t* K, const bf16_t* V, const bf16_t* PB, bf16_t* OF, bf16_t* OB, int half) {
;     ...
;                 {
;                     bf16x8 Rf[2];
; #pragma unroll
;                     for (int ks = 0; ks < 2; ++ks) { const f32x4 r0v = Rt[4 * p + 2 * ks], r1v = Rt[4 * p + 2 * ks + 1];
;                         const u32x4 wvv = {cvt_pk_bf16(r0v[0], r0v[1]), cvt_pk_bf16(r0v[2], r0v[3]), cvt_pk_bf16(r1v[0], r1v[1]), cvt_pk_bf16(r1v[2], r1v[3])};
;                         Rf[ks] = __builtin_bit_cast(bf16x8, wvv); }
;                     u32x4 qf[2][2];
;     ...
;                     SCAN_QREAD(0, 0);
; #pragma unroll
;                     for (int it = 0; it < 8; ++it) { if (it < 7) SCAN_QREAD((it + 1) & 1, it + 1);
; #pragma unroll
;                         for (int ks = 0; ks < 2; ++ks) Ot[it] = __builtin_amdgcn_mfma_f32_16x16x32_bf16(Rf[ks], __builtin_bit_cast(bf16x8, qf[it & 1][ks]), Ot[it], 0, 0, 0); }
;     ...
;                     __builtin_amdgcn_sched_group_barrier(0x100, 4, 0);
;                     __builtin_amdgcn_sched_group_barrier(0x100, 4, 0); __builtin_amdgcn_sched_group_barrier(0x8, 2, 0);
;                     __builtin_amdgcn_sched_group_barrier(0x100, 4, 0); __builtin_amdgcn_sched_group_barrier(0x8, 2, 0);
;                     __builtin_amdgcn_sched_group_barrier(0x100, 4, 0); __builtin_amdgcn_sched_group_barrier(0x8, 2, 0);
;                     __builtin_amdgcn_sched_group_barrier(0x100, 4, 0); __builtin_amdgcn_sched_group_barrier(0x8, 2, 0);
;                     __builtin_amdgcn_sched_group_barrier(0x100, 4, 0); __builtin_amdgcn_sched_group_barrier(0x8, 2, 0);
;                     __builtin_amdgcn_sched_group_barrier(0x100, 4, 0); __builtin_amdgcn_sched_group_barrier(0x8, 2, 0);
;                     __builtin_amdgcn_sched_group_barrier(0x100, 4, 0); __builtin_amdgcn_sched_group_barrier(0x8, 2, 0);
;                     __builtin_amdgcn_sched_group_barrier(0x8, 2, 0);
;                 }
;                 __builtin_amdgcn_sched_barrier(0);
;                 { s16x4 kl[2][4], kh[2][4];
;     ...
;                 SCAN_KREAD(0, 0);
; #pragma unroll
;                 for (int mt = 0; mt < 4; ++mt) { if (mt < 3) SCAN_KREAD((mt + 1) & 1, mt + 1);
;                     f32x4 acc = Rt[4 * p + mt] * c1;
; #pragma unroll
.LBB0_980:
	v_cvt_pk_bf16_f32 v156, v28, v29
	v_cvt_pk_bf16_f32 v157, v30, v31
	v_cvt_pk_bf16_f32 v158, v20, v21
	v_cvt_pk_bf16_f32 v159, v22, v23
	v_cvt_pk_bf16_f32 v194, v16, v17
	v_cvt_pk_bf16_f32 v195, v18, v19
	v_cvt_pk_bf16_f32 v196, v24, v25
	v_cvt_pk_bf16_f32 v197, v26, v27
	ds_read_b64 v[96:97], v223 offset:16384
	ds_read_b64 v[98:99], v224 offset:16384
	ds_read_b64 v[100:101], v225 offset:16384
	ds_read_b64 v[102:103], v226 offset:16384
	ds_read_b64 v[104:105], v223 offset:18432
	ds_read_b64 v[106:107], v224 offset:18432
	ds_read_b64 v[108:109], v225 offset:18432
	ds_read_b64 v[110:111], v226 offset:18432
	s_waitcnt lgkmcnt(6)
	v_mfma_f32_16x16x32_bf16 v[96:99], v[156:159], v[96:99], v[112:115]
	s_waitcnt lgkmcnt(4)
	v_mfma_f32_16x16x32_bf16 v[96:99], v[194:197], v[100:103], v[96:99]
	s_nop 0
	ds_read_b64 v[112:113], v223 offset:20480
	ds_read_b64 v[114:115], v224 offset:20480
	ds_read_b64 v[234:235], v225 offset:20480
	ds_read_b64 v[236:237], v226 offset:20480
	s_waitcnt lgkmcnt(6)
	v_mfma_f32_16x16x32_bf16 v[100:103], v[156:159], v[104:107], v[116:119]
	s_waitcnt lgkmcnt(4)
	v_mfma_f32_16x16x32_bf16 v[100:103], v[194:197], v[108:111], v[100:103]
	ds_read_b64 v[108:109], v223 offset:22528
	ds_read_b64 v[110:111], v224 offset:22528
	ds_read_b64 v[116:117], v225 offset:22528
	ds_read_b64 v[118:119], v226 offset:22528
	s_waitcnt lgkmcnt(6)
	v_mfma_f32_16x16x32_bf16 v[104:107], v[156:159], v[112:115], v[120:123]
	s_waitcnt lgkmcnt(4)
	v_mfma_f32_16x16x32_bf16 v[104:107], v[194:197], v[234:237], v[104:107]
	ds_read_b64 v[112:113], v223 offset:24576
	ds_read_b64 v[114:115], v224 offset:24576
	ds_read_b64 v[120:121], v225 offset:24576
	ds_read_b64 v[122:123], v226 offset:24576
	s_waitcnt lgkmcnt(6)
	v_mfma_f32_16x16x32_bf16 v[108:111], v[156:159], v[108:111], v[124:127]
	s_waitcnt lgkmcnt(4)
	v_mfma_f32_16x16x32_bf16 v[108:111], v[194:197], v[116:119], v[108:111]
	ds_read_b64 v[116:117], v223 offset:26624
	ds_read_b64 v[118:119], v224 offset:26624
	ds_read_b64 v[124:125], v225 offset:26624
	ds_read_b64 v[126:127], v226 offset:26624
	s_waitcnt lgkmcnt(6)
	v_mfma_f32_16x16x32_bf16 v[112:115], v[156:159], v[112:115], v[128:131]
	s_waitcnt lgkmcnt(4)
	v_mfma_f32_16x16x32_bf16 v[112:115], v[194:197], v[120:123], v[112:115]
	ds_read_b64 v[120:121], v223 offset:28672
	ds_read_b64 v[122:123], v224 offset:28672
	ds_read_b64 v[128:129], v225 offset:28672
	ds_read_b64 v[130:131], v226 offset:28672
	s_waitcnt lgkmcnt(6)
	v_mfma_f32_16x16x32_bf16 v[116:119], v[156:159], v[116:119], v[132:135]
	s_waitcnt lgkmcnt(4)
	v_mfma_f32_16x16x32_bf16 v[116:119], v[194:197], v[124:127], v[116:119]
	ds_read_b64 v[124:125], v223 offset:30720
	ds_read_b64 v[126:127], v224 offset:30720
	ds_read_b64 v[132:133], v225 offset:30720
	ds_read_b64 v[134:135], v226 offset:30720
	s_waitcnt lgkmcnt(6)
	v_mfma_f32_16x16x32_bf16 v[120:123], v[156:159], v[120:123], v[136:139]
	s_waitcnt lgkmcnt(4)
	v_mfma_f32_16x16x32_bf16 v[120:123], v[194:197], v[128:131], v[120:123]
	s_waitcnt lgkmcnt(2)
	v_mfma_f32_16x16x32_bf16 v[124:127], v[156:159], v[124:127], v[140:143]
	s_waitcnt lgkmcnt(0)
	v_mfma_f32_16x16x32_bf16 v[124:127], v[194:197], v[132:135], v[124:127]
	ds_read_b64_tr_b16 v[128:129], v227 offset:49152
	ds_read_b64_tr_b16 v[130:131], v228 offset:49664
	ds_read_b64_tr_b16 v[132:133], v227 offset:53248
	ds_read_b64_tr_b16 v[134:135], v228 offset:53760
	ds_read_b64_tr_b16 v[136:137], v227 offset:57344
	ds_read_b64_tr_b16 v[138:139], v228 offset:57856
	v_mul_f32_e32 v30, v144, v30
	v_mul_f32_e32 v31, v145, v31
	v_mul_f32_e32 v28, v146, v28
	v_mul_f32_e32 v29, v147, v29
	ds_read_b64_tr_b16 v[140:141], v227 offset:61440
	ds_read_b64_tr_b16 v[142:143], v228 offset:61952
	ds_read_b64_tr_b16 v[156:157], v229 offset:49152
	ds_read_b64_tr_b16 v[158:159], v230 offset:49664
	ds_read_b64_tr_b16 v[194:195], v229 offset:53248
	ds_read_b64_tr_b16 v[196:197], v230 offset:53760
	ds_read_b64_tr_b16 v[234:235], v229 offset:57344
	ds_read_b64_tr_b16 v[236:237], v230 offset:57856
	ds_read_b64_tr_b16 v[242:243], v229 offset:61440
	ds_read_b64_tr_b16 v[244:245], v230 offset:61952
	s_waitcnt lgkmcnt(14)
	v_mfma_f32_16x16x32_bf16 v[28:31], v[128:131], v[72:75], v[28:31]
	v_mul_f32_e32 v22, v144, v22
	v_mul_f32_e32 v23, v145, v23
	v_mul_f32_e32 v20, v146, v20
	v_mul_f32_e32 v21, v147, v21
	v_mul_f32_e32 v18, v144, v18
	v_mul_f32_e32 v19, v145, v19
	s_waitcnt lgkmcnt(12)
	v_mfma_f32_16x16x32_bf16 v[28:31], v[132:135], v[80:83], v[28:31]
	v_mul_f32_e32 v16, v146, v16
	v_mul_f32_e32 v17, v147, v17
	v_mul_f32_e32 v26, v144, v26
	v_mul_f32_e32 v27, v145, v27
	v_mul_f32_e32 v24, v146, v24
	v_mul_f32_e32 v25, v147, v25
	s_waitcnt lgkmcnt(10)
	v_mfma_f32_16x16x32_bf16 v[28:31], v[136:139], v[88:91], v[28:31]
	s_andn2_b64 vcc, exec, s[44:45]
	s_waitcnt lgkmcnt(8)
	v_mfma_f32_16x16x32_bf16 v[28:31], v[140:143], v[92:95], v[28:31]
	ds_read_b64_tr_b16 v[128:129], v231 offset:49152
	ds_read_b64_tr_b16 v[130:131], v232 offset:49664
	ds_read_b64_tr_b16 v[132:133], v231 offset:53248
	ds_read_b64_tr_b16 v[134:135], v232 offset:53760
	ds_read_b64_tr_b16 v[136:137], v231 offset:57344
	ds_read_b64_tr_b16 v[138:139], v232 offset:57856
	ds_read_b64_tr_b16 v[140:141], v231 offset:61440
	ds_read_b64_tr_b16 v[142:143], v232 offset:61952
	s_waitcnt lgkmcnt(14)
	v_mfma_f32_16x16x32_bf16 v[20:23], v[156:159], v[72:75], v[20:23]
	s_waitcnt lgkmcnt(12)
	v_mfma_f32_16x16x32_bf16 v[20:23], v[194:197], v[80:83], v[20:23]
	s_waitcnt lgkmcnt(10)
	v_mfma_f32_16x16x32_bf16 v[20:23], v[234:237], v[88:91], v[20:23]
	s_waitcnt lgkmcnt(8)
	v_mfma_f32_16x16x32_bf16 v[20:23], v[242:245], v[92:95], v[20:23]
	ds_read_b64_tr_b16 v[156:157], v233 offset:49152
	ds_read_b64_tr_b16 v[158:159], v241 offset:49664
	ds_read_b64_tr_b16 v[194:195], v233 offset:53248
	ds_read_b64_tr_b16 v[196:197], v241 offset:53760
	ds_read_b64_tr_b16 v[234:235], v233 offset:57344
	ds_read_b64_tr_b16 v[236:237], v241 offset:57856
	ds_read_b64_tr_b16 v[242:243], v233 offset:61440
	ds_read_b64_tr_b16 v[244:245], v241 offset:61952
	s_waitcnt lgkmcnt(14)
	v_mfma_f32_16x16x32_bf16 v[16:19], v[128:131], v[72:75], v[16:19]
	s_waitcnt lgkmcnt(0)
	s_barrier
	v_cndmask_b32_e64 v128, 0, 1, s[44:45]
	v_cmp_ne_u32_e64 s[34:35], 1, v128
	s_waitcnt lgkmcnt(12)
	v_mfma_f32_16x16x32_bf16 v[16:19], v[132:135], v[80:83], v[16:19]
	v_lshl_add_u64 v[128:129], v[148:149], 0, s[42:43]
	v_lshl_add_u64 v[130:131], v[150:151], 0, s[42:43]
	s_cbranch_vccnz .Lscan0_nodma
	s_waitcnt vmcnt(8)
	s_branch .Lscan0_wdone

; __device__ __forceinline__ void scan_phase(const Frame& F, const bf16_t* Q, const bf16_t* K, const bf16_t* V, const bf16_t* PB, bf16_t* OF, bf16_t* OB, int half) {
;     ...
;                 {
;                     bf16x8 Rf[2];
; #pragma unroll
;                     for (int ks = 0; ks < 2; ++ks) { const f32x4 r0v = Rt[4 * p + 2 * ks], r1v = Rt[4 * p + 2 * ks + 1];
;                         const u32x4 wvv = {cvt_pk_bf16(r0v[0], r0v[1]), cvt_pk_bf16(r0v[2], r0v[3]), cvt_pk_bf16(r1v[0], r1v[1]), cvt_pk_bf16(r1v[2], r1v[3])};
;                         Rf[ks] = __builtin_bit_cast(bf16x8, wvv); }
;                     u32x4 qf[2][2];
;     ...
;                     SCAN_QREAD(0, 0);
; #pragma unroll
;                     for (int it = 0; it < 8; ++it) { if (it < 7) SCAN_QREAD((it + 1) & 1, it + 1);
; #pragma unroll
;                         for (int ks = 0; ks < 2; ++ks) Ot[it] = __builtin_amdgcn_mfma_f32_16x16x32_bf16(Rf[ks], __builtin_bit_cast(bf16x8, qf[it & 1][ks]), Ot[it], 0, 0, 0); }
;     ...
;                     __builtin_amdgcn_sched_group_barrier(0x100, 4, 0);
;                     __builtin_amdgcn_sched_group_barrier(0x100, 4, 0); __builtin_amdgcn_sched_group_barrier(0x8, 2, 0);
;                     __builtin_amdgcn_sched_group_barrier(0x100, 4, 0); __builtin_amdgcn_sched_group_barrier(0x8, 2, 0);
;                     __builtin_amdgcn_sched_group_barrier(0x100, 4, 0); __builtin_amdgcn_sched_group_barrier(0x8, 2, 0);
;                     __builtin_amdgcn_sched_group_barrier(0x100, 4, 0); __builtin_amdgcn_sched_group_barrier(0x8, 2, 0);
;                     __builtin_amdgcn_sched_group_barrier(0x100, 4, 0); __builtin_amdgcn_sched_group_barrier(0x8, 2, 0);
;                     __builtin_amdgcn_sched_group_barrier(0x100, 4, 0); __builtin_amdgcn_sched_group_barrier(0x8, 2, 0);
;                     __builtin_amdgcn_sched_group_barrier(0x100, 4, 0); __builtin_amdgcn_sched_group_barrier(0x8, 2, 0);
;                     __builtin_amdgcn_sched_group_barrier(0x8, 2, 0);
;                 }
;                 __builtin_amdgcn_sched_barrier(0);
;                 { s16x4 kl[2][4], kh[2][4];
;     ...
;                 SCAN_KREAD(0, 0);
; #pragma unroll
;                 for (int mt = 0; mt < 4; ++mt) { if (mt < 3) SCAN_KREAD((mt + 1) & 1, mt + 1);
;                     f32x4 acc = Rt[4 * p + mt] * c1;
; #pragma unroll
.LBB0_982:
	v_cvt_pk_bf16_f32 v132, v12, v13
	v_cvt_pk_bf16_f32 v133, v14, v15
	v_cvt_pk_bf16_f32 v134, v8, v9
	v_cvt_pk_bf16_f32 v135, v10, v11
	v_cvt_pk_bf16_f32 v136, v4, v5
	v_cvt_pk_bf16_f32 v137, v6, v7
	v_cvt_pk_bf16_f32 v138, v0, v1
	v_cvt_pk_bf16_f32 v139, v2, v3
	ds_read_b64 v[140:141], v223
	ds_read_b64 v[142:143], v224
	ds_read_b64 v[156:157], v225
	ds_read_b64 v[158:159], v226
	ds_read_b64 v[194:195], v223 offset:2048
	ds_read_b64 v[196:197], v224 offset:2048
	ds_read_b64 v[234:235], v225 offset:2048
	ds_read_b64 v[236:237], v226 offset:2048
	s_waitcnt lgkmcnt(6)
	v_mfma_f32_16x16x32_bf16 v[96:99], v[132:135], v[140:143], v[96:99]
	s_waitcnt lgkmcnt(4)
	v_mfma_f32_16x16x32_bf16 v[96:99], v[136:139], v[156:159], v[96:99]
	ds_read_b64 v[140:141], v223 offset:4096
	ds_read_b64 v[142:143], v224 offset:4096
	ds_read_b64 v[156:157], v225 offset:4096
	ds_read_b64 v[158:159], v226 offset:4096
	s_waitcnt lgkmcnt(6)
	v_mfma_f32_16x16x32_bf16 v[100:103], v[132:135], v[194:197], v[100:103]
	s_waitcnt lgkmcnt(4)
	v_mfma_f32_16x16x32_bf16 v[100:103], v[136:139], v[234:237], v[100:103]
	ds_read_b64 v[194:195], v223 offset:6144
	ds_read_b64 v[196:197], v224 offset:6144
	ds_read_b64 v[234:235], v225 offset:6144
	ds_read_b64 v[236:237], v226 offset:6144
	s_waitcnt lgkmcnt(6)
	v_mfma_f32_16x16x32_bf16 v[104:107], v[132:135], v[140:143], v[104:107]
	s_waitcnt lgkmcnt(4)
	v_mfma_f32_16x16x32_bf16 v[104:107], v[136:139], v[156:159], v[104:107]
	ds_read_b64 v[140:141], v223 offset:8192
	ds_read_b64 v[142:143], v224 offset:8192
	ds_read_b64 v[156:157], v225 offset:8192
	ds_read_b64 v[158:159], v226 offset:8192
	s_waitcnt lgkmcnt(6)
	v_mfma_f32_16x16x32_bf16 v[108:111], v[132:135], v[194:197], v[108:111]
	s_waitcnt lgkmcnt(4)
	v_mfma_f32_16x16x32_bf16 v[108:111], v[136:139], v[234:237], v[108:111]
	ds_read_b64 v[194:195], v223 offset:10240
	ds_read_b64 v[196:197], v224 offset:10240
	ds_read_b64 v[234:235], v225 offset:10240
	ds_read_b64 v[236:237], v226 offset:10240
	s_waitcnt lgkmcnt(6)
	v_mfma_f32_16x16x32_bf16 v[112:115], v[132:135], v[140:143], v[112:115]
	s_waitcnt lgkmcnt(4)
	v_mfma_f32_16x16x32_bf16 v[112:115], v[136:139], v[156:159], v[112:115]
	ds_read_b64 v[140:141], v223 offset:12288
	ds_read_b64 v[142:143], v224 offset:12288
	ds_read_b64 v[156:157], v225 offset:12288
	ds_read_b64 v[158:159], v226 offset:12288
	s_waitcnt lgkmcnt(6)
	v_mfma_f32_16x16x32_bf16 v[116:119], v[132:135], v[194:197], v[116:119]
	s_waitcnt lgkmcnt(4)
	v_mfma_f32_16x16x32_bf16 v[116:119], v[136:139], v[234:237], v[116:119]
	ds_read_b64 v[194:195], v223 offset:14336
	ds_read_b64 v[196:197], v224 offset:14336
	ds_read_b64 v[234:235], v225 offset:14336
	ds_read_b64 v[236:237], v226 offset:14336
	s_waitcnt lgkmcnt(6)
	v_mfma_f32_16x16x32_bf16 v[120:123], v[132:135], v[140:143], v[120:123]
	s_waitcnt lgkmcnt(4)
	v_mfma_f32_16x16x32_bf16 v[120:123], v[136:139], v[156:159], v[120:123]
	s_waitcnt lgkmcnt(2)
	v_mfma_f32_16x16x32_bf16 v[124:127], v[132:135], v[194:197], v[124:127]
	s_waitcnt lgkmcnt(0)
	v_mfma_f32_16x16x32_bf16 v[124:127], v[136:139], v[234:237], v[124:127]
	ds_read_b64_tr_b16 v[132:133], v227 offset:32768
	ds_read_b64_tr_b16 v[134:135], v228 offset:33280
	ds_read_b64_tr_b16 v[136:137], v227 offset:36864
	ds_read_b64_tr_b16 v[138:139], v228 offset:37376
	v_mov_b32_e32 v145, v144
	ds_read_b64_tr_b16 v[140:141], v227 offset:40960
	ds_read_b64_tr_b16 v[142:143], v228 offset:41472
	v_mul_f32_e32 v14, v144, v14
	v_mul_f32_e32 v15, v145, v15
	v_mul_f32_e32 v12, v146, v12
	v_mul_f32_e32 v13, v147, v13
	ds_read_b64_tr_b16 v[156:157], v227 offset:45056
	ds_read_b64_tr_b16 v[158:159], v228 offset:45568
	ds_read_b64_tr_b16 v[194:195], v229 offset:32768
	ds_read_b64_tr_b16 v[196:197], v230 offset:33280
	ds_read_b64_tr_b16 v[234:235], v229 offset:36864
	ds_read_b64_tr_b16 v[236:237], v230 offset:37376
	ds_read_b64_tr_b16 v[242:243], v229 offset:40960
	ds_read_b64_tr_b16 v[244:245], v230 offset:41472
	ds_read_b64_tr_b16 v[246:247], v229 offset:45056
	ds_read_b64_tr_b16 v[248:249], v230 offset:45568
	s_waitcnt lgkmcnt(14)
	v_mfma_f32_16x16x32_bf16 v[12:15], v[132:135], v[72:75], v[12:15]
	v_mul_f32_e32 v10, v144, v10
	v_mul_f32_e32 v11, v145, v11
	v_mul_f32_e32 v8, v146, v8
	v_mul_f32_e32 v9, v147, v9
	v_mul_f32_e32 v6, v144, v6
	v_mul_f32_e32 v7, v145, v7
	s_waitcnt lgkmcnt(12)
	v_mfma_f32_16x16x32_bf16 v[12:15], v[136:139], v[80:83], v[12:15]
	v_mul_f32_e32 v4, v146, v4
	v_mul_f32_e32 v5, v147, v5
	v_mul_f32_e32 v2, v144, v2
	v_mul_f32_e32 v3, v145, v3
	v_mul_f32_e32 v0, v146, v0
	v_mul_f32_e32 v1, v147, v1
	s_waitcnt lgkmcnt(10)
	v_mfma_f32_16x16x32_bf16 v[12:15], v[140:143], v[88:91], v[12:15]
	s_and_b64 vcc, exec, s[34:35]
	s_waitcnt lgkmcnt(8)
	v_mfma_f32_16x16x32_bf16 v[12:15], v[156:159], v[92:95], v[12:15]
	ds_read_b64_tr_b16 v[132:133], v231 offset:32768
	ds_read_b64_tr_b16 v[134:135], v232 offset:33280
	ds_read_b64_tr_b16 v[136:137], v231 offset:36864
	ds_read_b64_tr_b16 v[138:139], v232 offset:37376
	ds_read_b64_tr_b16 v[140:141], v231 offset:40960
	ds_read_b64_tr_b16 v[142:143], v232 offset:41472
	ds_read_b64_tr_b16 v[156:157], v231 offset:45056
	ds_read_b64_tr_b16 v[158:159], v232 offset:45568
	s_waitcnt lgkmcnt(14)
	v_mfma_f32_16x16x32_bf16 v[8:11], v[194:197], v[72:75], v[8:11]
	s_waitcnt lgkmcnt(12)
	v_mfma_f32_16x16x32_bf16 v[8:11], v[234:237], v[80:83], v[8:11]
	s_waitcnt lgkmcnt(10)
	v_mfma_f32_16x16x32_bf16 v[8:11], v[242:245], v[88:91], v[8:11]
	s_waitcnt lgkmcnt(8)
	v_mfma_f32_16x16x32_bf16 v[8:11], v[246:249], v[92:95], v[8:11]
	ds_read_b64_tr_b16 v[194:195], v233 offset:32768
	ds_read_b64_tr_b16 v[196:197], v241 offset:33280
	ds_read_b64_tr_b16 v[234:235], v233 offset:36864
	ds_read_b64_tr_b16 v[236:237], v241 offset:37376
	ds_read_b64_tr_b16 v[242:243], v233 offset:40960
	ds_read_b64_tr_b16 v[244:245], v241 offset:41472
	ds_read_b64_tr_b16 v[246:247], v233 offset:45056
	ds_read_b64_tr_b16 v[248:249], v241 offset:45568
	s_waitcnt lgkmcnt(14)
	v_mfma_f32_16x16x32_bf16 v[4:7], v[132:135], v[72:75], v[4:7]
	s_waitcnt lgkmcnt(0)
	s_barrier
; __device__ __forceinline__ bf16x8 pack8(s16x4 lo, s16x4 hi) { return (bf16x8){lo[0], lo[1], lo[2], lo[3], hi[0], hi[1], hi[2], hi[3]}; }
; #define SCAN_LOAD_QK(cc, pq) do { const size_t u0_ = (rb + (size_t)(cc) * 128) * 2048 + head * 256 + (pq) * 64;     \
;             _Pragma("unroll") for (int ii = 0; ii < 2; ++ii) { rq[ii] = *(const GAS u32x4*)(Q + u0_ + (size_t)ii * 64 * 2048 + lqk_l); rk[ii] = *(const GAS u32x4*)(K + u0_ + (size_t)ii * 64 * 2048 + lqk_l); } } while (0)
; #define SCAN_WRITE_QK(par) do { _Pragma("unroll") for (int ii = 0; ii < 2; ++ii) { *(LAS u32x4*)(bSt + ((par) ? LQ1 : LQ0) + ii * 64 * QS) = rq[ii]; *(LAS u32x4*)(bSt + ((par) ? LK1 : LK0) + ii * 64 * QS) = rk[ii]; } } while (0)
; #define SCAN_KREAD(b_, mt_) do { _Pragma("unroll") for (int ks = 0; ks < 4; ++ks) { const int ko = ((p & 1) ? LK1 : LK0) + 32 * ks * QS; kl[b_][ks] = tr_read(bKlo[mt_] + ko); kh[b_][ks] = tr_read(bKhi[mt_] + ko); } } while (0)
; __device__ __forceinline__ void scan_phase(const Frame& F, const bf16_t* Q, const bf16_t* K, const bf16_t* V, const bf16_t* PB, bf16_t* OF, bf16_t* OB, int half) {
;     ...
;                 if (p < 3 || more) SCAN_WRITE_QK((p + 1) & 1);
;                 if (p == 1 && more) SCAN_DMA_VP(cn);
;                 if (p < 2) SCAN_LOAD_QK(c, p + 2); else if (more) SCAN_LOAD_QK(cn, p - 2);
;     ...
;                 for (int mt = 0; mt < 4; ++mt) { if (mt < 3) SCAN_KREAD((mt + 1) & 1, mt + 1);
;                     f32x4 acc = Rt[4 * p + mt] * c1;
; #pragma unroll
;                     for (int ks = 0; ks < 4; ++ks) acc = __builtin_amdgcn_mfma_f32_16x16x32_bf16(pack8(kl[mt & 1][ks], kh[mt & 1][ks]), Vf[ks], acc, 0, 0, 0);
;                     Rt[4 * p + mt] = acc; }
;     ...
;                 __builtin_amdgcn_sched_group_barrier(0x100, 8, 0);
;                 __builtin_amdgcn_sched_group_barrier(0x100, 8, 0); __builtin_amdgcn_sched_group_barrier(0x8, 4, 0);
;                 __builtin_amdgcn_sched_group_barrier(0x100, 8, 0); __builtin_amdgcn_sched_group_barrier(0x8, 4, 0);
;                 __builtin_amdgcn_sched_group_barrier(0x100, 8, 0); __builtin_amdgcn_sched_group_barrier(0x8, 4, 0);
;                 __builtin_amdgcn_sched_group_barrier(0x8, 4, 0);
;                 }
	s_waitcnt lgkmcnt(12)
	v_mfma_f32_16x16x32_bf16 v[4:7], v[136:139], v[80:83], v[4:7]
	s_waitcnt lgkmcnt(10)
	v_mfma_f32_16x16x32_bf16 v[4:7], v[140:143], v[88:91], v[4:7]
	s_waitcnt lgkmcnt(8)
	v_mfma_f32_16x16x32_bf16 v[4:7], v[156:159], v[92:95], v[4:7]
	s_waitcnt lgkmcnt(6)
	v_mfma_f32_16x16x32_bf16 v[0:3], v[194:197], v[72:75], v[0:3]
	s_waitcnt lgkmcnt(4)
	v_mfma_f32_16x16x32_bf16 v[0:3], v[234:237], v[80:83], v[0:3]
	s_waitcnt lgkmcnt(2)
	v_mfma_f32_16x16x32_bf16 v[0:3], v[242:245], v[88:91], v[0:3]
	s_waitcnt lgkmcnt(0)
	v_mfma_f32_16x16x32_bf16 v[0:3], v[246:249], v[92:95], v[0:3]
	s_cbranch_vccnz .LBB0_977
	s_waitcnt vmcnt(3)
	ds_write_b128 v214, v[64:67]
	s_waitcnt vmcnt(2)
	ds_write_b128 v214, v[68:71] offset:32768
	s_waitcnt vmcnt(1)
	ds_write_b128 v214, v[76:79] offset:8192
	s_waitcnt vmcnt(0)
	ds_write_b128 v214, v[84:87] offset:40960
	v_add_co_u32_e32 v64, vcc, 0x10700000, v130
	s_nop 1
	v_addc_co_u32_e32 v65, vcc, 0, v131, vcc
	v_add_co_u32_e32 v68, vcc, 0x4a800000, v128
	global_load_dwordx4 v[64:67], v[64:65], off offset:128
	s_nop 0
	v_addc_co_u32_e32 v69, vcc, 0, v129, vcc
	v_add_co_u32_e32 v76, vcc, 0x10740000, v130
	global_load_dwordx4 v[68:71], v[68:69], off offset:128
	s_nop 0
	v_addc_co_u32_e32 v77, vcc, 0, v131, vcc
	v_add_co_u32_e32 v84, vcc, 0x4a840000, v128
	global_load_dwordx4 v[76:79], v[76:77], off offset:128
	s_nop 0
	v_addc_co_u32_e32 v85, vcc, 0, v129, vcc
	global_load_dwordx4 v[84:87], v[84:85], off offset:128
	s_branch .LBB0_977

; __device__ __forceinline__ void scan_phase(const Frame& F, const bf16_t* Q, const bf16_t* K, const bf16_t* V, const bf16_t* PB, bf16_t* OF, bf16_t* OB, int half) {
;     ...
;                 {
;                     bf16x8 Rf[2];
; #pragma unroll
;                     for (int ks = 0; ks < 2; ++ks) { const f32x4 r0v = Rt[4 * p + 2 * ks], r1v = Rt[4 * p + 2 * ks + 1];
;                         const u32x4 wvv = {cvt_pk_bf16(r0v[0], r0v[1]), cvt_pk_bf16(r0v[2], r0v[3]), cvt_pk_bf16(r1v[0], r1v[1]), cvt_pk_bf16(r1v[2], r1v[3])};
;                         Rf[ks] = __builtin_bit_cast(bf16x8, wvv); }
;                     u32x4 qf[2][2];
;     ...
;                     SCAN_QREAD(0, 0);
; #pragma unroll
;                     for (int it = 0; it < 8; ++it) { if (it < 7) SCAN_QREAD((it + 1) & 1, it + 1);
; #pragma unroll
;                         for (int ks = 0; ks < 2; ++ks) Ot[it] = __builtin_amdgcn_mfma_f32_16x16x32_bf16(Rf[ks], __builtin_bit_cast(bf16x8, qf[it & 1][ks]), Ot[it], 0, 0, 0); }
;     ...
;                     __builtin_amdgcn_sched_group_barrier(0x100, 4, 0);
;                     __builtin_amdgcn_sched_group_barrier(0x100, 4, 0); __builtin_amdgcn_sched_group_barrier(0x8, 2, 0);
;                     __builtin_amdgcn_sched_group_barrier(0x100, 4, 0); __builtin_amdgcn_sched_group_barrier(0x8, 2, 0);
;                     __builtin_amdgcn_sched_group_barrier(0x100, 4, 0); __builtin_amdgcn_sched_group_barrier(0x8, 2, 0);
;                     __builtin_amdgcn_sched_group_barrier(0x100, 4, 0); __builtin_amdgcn_sched_group_barrier(0x8, 2, 0);
;                     __builtin_amdgcn_sched_group_barrier(0x100, 4, 0); __builtin_amdgcn_sched_group_barrier(0x8, 2, 0);
;                     __builtin_amdgcn_sched_group_barrier(0x100, 4, 0); __builtin_amdgcn_sched_group_barrier(0x8, 2, 0);
;                     __builtin_amdgcn_sched_group_barrier(0x100, 4, 0); __builtin_amdgcn_sched_group_barrier(0x8, 2, 0);
;                     __builtin_amdgcn_sched_group_barrier(0x8, 2, 0);
;                 }
;                 __builtin_amdgcn_sched_barrier(0);
;                 { s16x4 kl[2][4], kh[2][4];
;     ...
;                 SCAN_KREAD(0, 0);
; #pragma unroll
;                 for (int mt = 0; mt < 4; ++mt) { if (mt < 3) SCAN_KREAD((mt + 1) & 1, mt + 1);
;                     f32x4 acc = Rt[4 * p + mt] * c1;
; #pragma unroll
.LBB0_987:
	v_add_u32_e32 v128, 1, v192
	v_cvt_f32_i32_e32 v229, v128
	v_cvt_pk_bf16_f32 v140, v48, v49
	v_cvt_pk_bf16_f32 v141, v50, v51
	v_cvt_pk_bf16_f32 v142, v52, v53
	v_cvt_pk_bf16_f32 v143, v54, v55
	v_cvt_pk_bf16_f32 v150, v56, v57
	v_cvt_pk_bf16_f32 v151, v58, v59
	v_cvt_pk_bf16_f32 v152, v60, v61
	v_cvt_pk_bf16_f32 v153, v62, v63
	ds_read_b64 v[128:129], v217 offset:16384
	ds_read_b64 v[130:131], v218 offset:16384
	ds_read_b64 v[132:133], v219 offset:16384
	ds_read_b64 v[134:135], v220 offset:16384
	ds_read_b64 v[136:137], v217 offset:18432
	ds_read_b64 v[138:139], v218 offset:18432
	ds_read_b64 v[194:195], v219 offset:18432
	ds_read_b64 v[196:197], v220 offset:18432
	s_waitcnt lgkmcnt(6)
	v_mfma_f32_16x16x32_bf16 v[96:99], v[140:143], v[128:131], v[96:99]
	s_waitcnt lgkmcnt(4)
	v_mfma_f32_16x16x32_bf16 v[132:135], v[150:153], v[132:135], v[96:99]
	s_nop 5
	ds_read_b64 v[96:97], v217 offset:20480
	ds_read_b64 v[98:99], v218 offset:20480
	ds_read_b64 v[128:129], v219 offset:20480
	ds_read_b64 v[130:131], v220 offset:20480
	s_waitcnt lgkmcnt(6)
	v_mfma_f32_16x16x32_bf16 v[100:103], v[140:143], v[136:139], v[100:103]
	s_waitcnt lgkmcnt(4)
	v_mfma_f32_16x16x32_bf16 v[136:139], v[150:153], v[194:197], v[100:103]
	s_nop 5
	ds_read_b64 v[100:101], v217 offset:22528
	ds_read_b64 v[102:103], v218 offset:22528
	ds_read_b64 v[194:195], v219 offset:22528
	ds_read_b64 v[196:197], v220 offset:22528
	s_waitcnt lgkmcnt(6)
	v_mfma_f32_16x16x32_bf16 v[96:99], v[140:143], v[96:99], v[104:107]
	s_waitcnt lgkmcnt(4)
	v_mfma_f32_16x16x32_bf16 v[128:131], v[150:153], v[128:131], v[96:99]
	s_nop 5
	ds_read_b64 v[96:97], v217 offset:24576
	ds_read_b64 v[98:99], v218 offset:24576
	ds_read_b64 v[104:105], v219 offset:24576
	ds_read_b64 v[106:107], v220 offset:24576
	s_waitcnt lgkmcnt(6)
	v_mfma_f32_16x16x32_bf16 v[100:103], v[140:143], v[100:103], v[108:111]
	s_waitcnt lgkmcnt(4)
	v_mfma_f32_16x16x32_bf16 v[108:111], v[150:153], v[194:197], v[100:103]
	s_nop 5
	ds_read_b64 v[100:101], v217 offset:26624
	ds_read_b64 v[102:103], v218 offset:26624
	ds_read_b64 v[194:195], v219 offset:26624
	ds_read_b64 v[196:197], v220 offset:26624
	s_waitcnt lgkmcnt(6)
	v_mfma_f32_16x16x32_bf16 v[96:99], v[140:143], v[96:99], v[112:115]
	s_waitcnt lgkmcnt(4)
	v_mfma_f32_16x16x32_bf16 v[104:107], v[150:153], v[104:107], v[96:99]
	s_nop 5
	ds_read_b64 v[96:97], v217 offset:28672
	ds_read_b64 v[98:99], v218 offset:28672
	ds_read_b64 v[112:113], v219 offset:28672
	ds_read_b64 v[114:115], v220 offset:28672
	s_waitcnt lgkmcnt(6)
	v_mfma_f32_16x16x32_bf16 v[100:103], v[140:143], v[100:103], v[116:119]
	s_waitcnt lgkmcnt(4)
	v_mfma_f32_16x16x32_bf16 v[100:103], v[150:153], v[194:197], v[100:103]
	s_nop 0
	ds_read_b64 v[116:117], v217 offset:30720
	ds_read_b64 v[118:119], v218 offset:30720
	ds_read_b64 v[194:195], v219 offset:30720
	ds_read_b64 v[196:197], v220 offset:30720
	s_waitcnt lgkmcnt(6)
	v_mfma_f32_16x16x32_bf16 v[96:99], v[140:143], v[96:99], v[120:123]
	s_waitcnt lgkmcnt(4)
	v_mfma_f32_16x16x32_bf16 v[96:99], v[150:153], v[112:115], v[96:99]
	s_waitcnt lgkmcnt(2)
	v_mfma_f32_16x16x32_bf16 v[112:115], v[140:143], v[116:119], v[124:127]
	s_waitcnt lgkmcnt(0)
	v_mfma_f32_16x16x32_bf16 v[112:115], v[150:153], v[194:197], v[112:115]
	ds_read_b64_tr_b16 v[116:117], v221 offset:49152
	ds_read_b64_tr_b16 v[118:119], v222 offset:49664
	ds_read_b64_tr_b16 v[120:121], v221 offset:53248
	ds_read_b64_tr_b16 v[122:123], v222 offset:53760
	ds_read_b64_tr_b16 v[124:125], v221 offset:57344
	ds_read_b64_tr_b16 v[126:127], v222 offset:57856
	v_mul_f32_e32 v50, v144, v50
	v_mul_f32_e32 v51, v145, v51
	v_mul_f32_e32 v48, v146, v48
	v_mul_f32_e32 v49, v147, v49
	ds_read_b64_tr_b16 v[140:141], v221 offset:61440
	ds_read_b64_tr_b16 v[142:143], v222 offset:61952
	ds_read_b64_tr_b16 v[150:151], v223 offset:49152
	ds_read_b64_tr_b16 v[152:153], v224 offset:49664
	ds_read_b64_tr_b16 v[194:195], v223 offset:53248
	ds_read_b64_tr_b16 v[196:197], v224 offset:53760
	ds_read_b64_tr_b16 v[218:219], v223 offset:57344
	ds_read_b64_tr_b16 v[220:221], v224 offset:57856
	ds_read_b64_tr_b16 v[230:231], v223 offset:61440
	ds_read_b64_tr_b16 v[232:233], v224 offset:61952
	s_waitcnt lgkmcnt(14)
	v_mfma_f32_16x16x32_bf16 v[48:51], v[116:119], v[72:75], v[48:51]
	v_mul_f32_e32 v54, v144, v54
	v_mul_f32_e32 v55, v145, v55
	v_mul_f32_e32 v52, v146, v52
	v_mul_f32_e32 v53, v147, v53
	v_mul_f32_e32 v58, v144, v58
	v_mul_f32_e32 v59, v145, v59
	s_waitcnt lgkmcnt(12)
	v_mfma_f32_16x16x32_bf16 v[48:51], v[120:123], v[80:83], v[48:51]
	v_mul_f32_e32 v56, v146, v56
	v_mul_f32_e32 v57, v147, v57
	v_mul_f32_e32 v62, v144, v62
	v_mul_f32_e32 v63, v145, v63
	v_mul_f32_e32 v60, v146, v60
	v_mul_f32_e32 v61, v147, v61
	s_waitcnt lgkmcnt(10)
	v_mfma_f32_16x16x32_bf16 v[48:51], v[124:127], v[88:91], v[48:51]
	s_add_u32 s12, s62, s41
	v_lshl_add_u32 v192, v192, 12, v213
	s_addc_u32 s13, s63, s42
	s_waitcnt lgkmcnt(8)
	v_mfma_f32_16x16x32_bf16 v[48:51], v[140:143], v[92:95], v[48:51]
	ds_read_b64_tr_b16 v[116:117], v225 offset:49152
	ds_read_b64_tr_b16 v[118:119], v226 offset:49664
	ds_read_b64_tr_b16 v[120:121], v225 offset:53248
	ds_read_b64_tr_b16 v[122:123], v226 offset:53760
	ds_read_b64_tr_b16 v[124:125], v225 offset:57344
	ds_read_b64_tr_b16 v[126:127], v226 offset:57856
	ds_read_b64_tr_b16 v[140:141], v225 offset:61440
	ds_read_b64_tr_b16 v[142:143], v226 offset:61952
	s_waitcnt lgkmcnt(14)
	v_mfma_f32_16x16x32_bf16 v[52:55], v[150:153], v[72:75], v[52:55]
	s_add_u32 s30, s30, 0x100000
	s_addc_u32 s31, s31, 0
	s_add_u32 s41, s41, 0x100000
	s_waitcnt lgkmcnt(12)
; #define GAS __attribute__((address_space(1)))
; __device__ __forceinline__ unsigned cvt_pk_bf16(float lo, float hi) { unsigned r; asm volatile("v_cvt_pk_bf16_f32 %0, %1, %2" : "=v"(r) : "v"(lo), "v"(hi)); return r; }
; __device__ __forceinline__ bf16x8 pack8(s16x4 lo, s16x4 hi) { return (bf16x8){lo[0], lo[1], lo[2], lo[3], hi[0], hi[1], hi[2], hi[3]}; }
; #define SCAN_BAR() asm volatile("s_waitcnt lgkmcnt(0)\n\ts_barrier" ::: "memory")
; #define SCAN_KREAD(b_, mt_) do { _Pragma("unroll") for (int ks = 0; ks < 4; ++ks) { const int ko = ((p & 1) ? LK1 : LK0) + 32 * ks * QS; kl[b_][ks] = tr_read(bKlo[mt_] + ko); kh[b_][ks] = tr_read(bKhi[mt_] + ko); } } while (0)
; __device__ __forceinline__ void scan_phase(const Frame& F, const bf16_t* Q, const bf16_t* K, const bf16_t* V, const bf16_t* PB, bf16_t* OF, bf16_t* OB, int half) {
;     ...
;                 for (int mt = 0; mt < 4; ++mt) { if (mt < 3) SCAN_KREAD((mt + 1) & 1, mt + 1);
;                     f32x4 acc = Rt[4 * p + mt] * c1;
; #pragma unroll
;                     for (int ks = 0; ks < 4; ++ks) acc = __builtin_amdgcn_mfma_f32_16x16x32_bf16(pack8(kl[mt & 1][ks], kh[mt & 1][ks]), Vf[ks], acc, 0, 0, 0);
;                     Rt[4 * p + mt] = acc; }
;     ...
;                 __builtin_amdgcn_sched_group_barrier(0x100, 8, 0);
;                 __builtin_amdgcn_sched_group_barrier(0x100, 8, 0); __builtin_amdgcn_sched_group_barrier(0x8, 4, 0);
;                 __builtin_amdgcn_sched_group_barrier(0x100, 8, 0); __builtin_amdgcn_sched_group_barrier(0x8, 4, 0);
;                 __builtin_amdgcn_sched_group_barrier(0x100, 8, 0); __builtin_amdgcn_sched_group_barrier(0x8, 4, 0);
;                 __builtin_amdgcn_sched_group_barrier(0x8, 4, 0);
;                 }
;                 if (p == 3) {
;                     bf16_t* ob_ = O + r0 * 4096 + head * 512 + vq * 128; const unsigned lo_ = (unsigned)(l15_l * 4096 + 16 * wv + 4 * quad);
;                     float fi = __builtin_amdgcn_exp2f(lg2 * (float)(dir ? 128 - l15_l : l15_l + 1));
; #pragma unroll
;                     for (int it = 0; it < 8; ++it) {
;                         *(GAS u32x2*)(ob_ + (size_t)(16 * it) * 4096 + lo_) = (u32x2){cvt_pk_bf16(Ot[it][0] * fi, Ot[it][1] * fi), cvt_pk_bf16(Ot[it][2] * fi, Ot[it][3] * fi)}; fi *= gm16; }
;                 }
;                 SCAN_BAR();
	v_mfma_f32_16x16x32_bf16 v[52:55], v[194:197], v[80:83], v[52:55]
	s_addc_u32 s42, s42, 0
	v_lshl_add_u64 v[148:149], v[148:149], 0, s[24:25]
	s_cmp_eq_u32 s73, s43
	s_waitcnt lgkmcnt(10)
	v_mfma_f32_16x16x32_bf16 v[52:55], v[218:221], v[88:91], v[52:55]
	s_mov_b32 s44, s43
	s_waitcnt lgkmcnt(8)
	v_mfma_f32_16x16x32_bf16 v[52:55], v[230:233], v[92:95], v[52:55]
	ds_read_b64_tr_b16 v[150:151], v227 offset:49152
	ds_read_b64_tr_b16 v[152:153], v228 offset:49664
	ds_read_b64_tr_b16 v[194:195], v227 offset:53248
	ds_read_b64_tr_b16 v[196:197], v228 offset:53760
	ds_read_b64_tr_b16 v[218:219], v227 offset:57344
	ds_read_b64_tr_b16 v[220:221], v228 offset:57856
	ds_read_b64_tr_b16 v[222:223], v227 offset:61440
	ds_read_b64_tr_b16 v[224:225], v228 offset:61952
	s_waitcnt lgkmcnt(14)
	v_mfma_f32_16x16x32_bf16 v[56:59], v[116:119], v[72:75], v[56:59]
	s_waitcnt lgkmcnt(12)
	v_mfma_f32_16x16x32_bf16 v[56:59], v[120:123], v[80:83], v[56:59]
	s_waitcnt lgkmcnt(10)
	v_mfma_f32_16x16x32_bf16 v[56:59], v[124:127], v[88:91], v[56:59]
	s_waitcnt lgkmcnt(8)
	v_mfma_f32_16x16x32_bf16 v[56:59], v[140:143], v[92:95], v[56:59]
	s_waitcnt lgkmcnt(6)
	v_mfma_f32_16x16x32_bf16 v[60:63], v[150:153], v[72:75], v[60:63]
	v_mul_f32_e32 v72, s54, v229
	s_waitcnt lgkmcnt(4)
	v_mfma_f32_16x16x32_bf16 v[60:63], v[194:197], v[80:83], v[60:63]
	v_exp_f32_e32 v82, v72
	v_lshl_add_u64 v[72:73], v[192:193], 1, s[12:13]
	s_mov_b32 s12, 0x3a120000
	s_waitcnt lgkmcnt(2)
	v_mfma_f32_16x16x32_bf16 v[60:63], v[218:221], v[88:91], v[60:63]
	v_mul_f32_e32 v74, v82, v132
	v_mul_f32_e32 v75, v82, v133
	v_cvt_pk_bf16_f32 v74, v74, v75
	v_mul_f32_e32 v75, v82, v134
	v_mul_f32_e32 v80, v82, v135
	v_cvt_pk_bf16_f32 v75, v75, v80
	v_add_co_u32_e32 v80, vcc, s97, v72
	v_mul_f32_e32 v82, s37, v82
	s_nop 0
	v_addc_co_u32_e32 v81, vcc, 0, v73, vcc
	global_store_dwordx2 v[80:81], v[74:75], off
	v_mul_f32_e32 v74, v82, v136
	v_mul_f32_e32 v75, v82, v137
	v_cvt_pk_bf16_f32 v74, v74, v75
	v_mul_f32_e32 v75, v82, v138
	v_mul_f32_e32 v80, v82, v139
	v_cvt_pk_bf16_f32 v75, v75, v80
	v_add_co_u32_e32 v80, vcc, s12, v72
	v_mul_f32_e32 v82, s37, v82
	s_nop 0
	v_addc_co_u32_e32 v81, vcc, 0, v73, vcc
	global_store_dwordx2 v[80:81], v[74:75], off
	v_mul_f32_e32 v74, v82, v128
	v_mul_f32_e32 v75, v82, v129
	v_cvt_pk_bf16_f32 v74, v74, v75
	v_mul_f32_e32 v75, v82, v130
	v_mul_f32_e32 v80, v82, v131
	s_mov_b32 s12, 0x3a140000
	v_cvt_pk_bf16_f32 v75, v75, v80
	v_add_co_u32_e32 v80, vcc, s12, v72
	v_mul_f32_e32 v82, s37, v82
	s_nop 0
	v_addc_co_u32_e32 v81, vcc, 0, v73, vcc
	global_store_dwordx2 v[80:81], v[74:75], off
	v_mul_f32_e32 v74, v82, v108
	v_mul_f32_e32 v75, v82, v109
	v_cvt_pk_bf16_f32 v74, v74, v75
	v_mul_f32_e32 v75, v82, v110
	v_mul_f32_e32 v80, v82, v111
	s_mov_b32 s12, 0x3a160000
	v_cvt_pk_bf16_f32 v75, v75, v80
	v_add_co_u32_e32 v80, vcc, s12, v72
	v_mul_f32_e32 v82, s37, v82
	s_nop 0
	v_addc_co_u32_e32 v81, vcc, 0, v73, vcc
	global_store_dwordx2 v[80:81], v[74:75], off
	v_mul_f32_e32 v74, v82, v104
	v_mul_f32_e32 v75, v82, v105
	v_cvt_pk_bf16_f32 v74, v74, v75
	v_mul_f32_e32 v75, v82, v106
	v_mul_f32_e32 v80, v82, v107
	s_mov_b32 s12, 0x3a180000
	v_cvt_pk_bf16_f32 v75, v75, v80
	v_add_co_u32_e32 v80, vcc, s12, v72
	v_mul_f32_e32 v82, s37, v82
	s_nop 0
	v_addc_co_u32_e32 v81, vcc, 0, v73, vcc
	global_store_dwordx2 v[80:81], v[74:75], off
	v_mul_f32_e32 v74, v82, v100
	v_mul_f32_e32 v75, v82, v101
	v_cvt_pk_bf16_f32 v74, v74, v75
	v_mul_f32_e32 v75, v82, v102
	v_mul_f32_e32 v80, v82, v103
	s_mov_b32 s12, 0x3a1a0000
	v_cvt_pk_bf16_f32 v75, v75, v80
	v_add_co_u32_e32 v80, vcc, s12, v72
	v_mul_f32_e32 v82, s37, v82
	s_nop 0
	v_addc_co_u32_e32 v81, vcc, 0, v73, vcc
	global_store_dwordx2 v[80:81], v[74:75], off
	v_mul_f32_e32 v74, v82, v96
	v_mul_f32_e32 v75, v82, v97
	v_cvt_pk_bf16_f32 v74, v74, v75
	v_mul_f32_e32 v75, v82, v98
	v_mul_f32_e32 v80, v82, v99
	s_mov_b32 s12, 0x3a1c0000
	v_cvt_pk_bf16_f32 v75, v75, v80
	v_add_co_u32_e32 v80, vcc, s12, v72
	s_mov_b32 s12, 0x3a1e0000
	s_nop 0
	v_addc_co_u32_e32 v81, vcc, 0, v73, vcc
	global_store_dwordx2 v[80:81], v[74:75], off
	v_mul_f32_e32 v75, s37, v82
	v_mul_f32_e32 v74, v75, v112
	v_mul_f32_e32 v80, v75, v113
	v_add_co_u32_e32 v72, vcc, s12, v72
	v_cvt_pk_bf16_f32 v74, v74, v80
	v_mul_f32_e32 v80, v75, v114
	v_mul_f32_e32 v75, v75, v115
	v_addc_co_u32_e32 v73, vcc, 0, v73, vcc
	s_waitcnt lgkmcnt(0)
	v_mfma_f32_16x16x32_bf16 v[60:63], v[222:225], v[92:95], v[60:63]
	v_cvt_pk_bf16_f32 v75, v80, v75
	global_store_dwordx2 v[72:73], v[74:75], off
	s_waitcnt lgkmcnt(0)
	s_barrier
	s_cbranch_scc1 .LBB0_974
	.p2align 6
; #define LAS __attribute__((address_space(3)))
; __device__ __forceinline__ s16x4 tr_read(LAS unsigned char* p) { return __builtin_bit_cast(s16x4, __builtin_amdgcn_ds_read_tr16_b64_v4i16((LAS v4i16_t*)p)); }
; __device__ __forceinline__ bf16x8 pack8(s16x4 lo, s16x4 hi) { return (bf16x8){lo[0], lo[1], lo[2], lo[3], hi[0], hi[1], hi[2], hi[3]}; }
; template <int M, int N, class Fn> __device__ __forceinline__ void mattn_sfor(Fn&& f) { if constexpr (M < N) { f(std::integral_constant<int, M>{}); mattn_sfor<M + 1, N>(f); } }
; __device__ __forceinline__ void scan_phase(const Frame& F, const bf16_t* Q, const bf16_t* K, const bf16_t* V, const bf16_t* PB, bf16_t* OF, bf16_t* OB, int half) {
;     ...
;             for (int p = 0; p < 4; ++p) {
;                 if (p < 3 || more) SCAN_WRITE_QK((p + 1) & 1);
;                 if (p == 1 && more) SCAN_DMA_VP(cn);
;                 if (p < 2) SCAN_LOAD_QK(c, p + 2); else if (more) SCAN_LOAD_QK(cn, p - 2);
;                 if (p == 0) {
; #pragma unroll
;                     for (int ks = 0; ks < 4; ++ks) { const s16x4 lo = tr_read(bVlo + 32 * ks * 256), hi = tr_read(bVhi + 32 * ks * 256); Vf[ks] = pack8(lo, hi); }
;                     __builtin_amdgcn_sched_barrier(0);
;                     { u32x4 pwb[2];
;                       { constexpr int q0_ = pv_pair(dir, 0); pwb[0] = *(const LAS u32x4*)(bPk[q0_ & 3] + 16 * (q0_ >> 2) * 256); }
;                       __builtin_amdgcn_sched_group_barrier(0x100, 1, 0);
;                       mattn_sfor<0, 20>([&](auto n_) { constexpr int n = decltype(n_)::value, pr = pv_pair(dir, n), it = pr >> 2, ks = pr & 3, dks = ks - (it >> 1);
;                           if constexpr (n + 1 < 20) { constexpr int nx = pv_pair(dir, n + 1); pwb[(n + 1) & 1] = *(const LAS u32x4*)(bPk[nx & 3] + 16 * (nx >> 2) * 256); }
;                           u32x4 pw = pwb[n & 1];
;                           if constexpr (dks == 0) { pw.x &= pmk[it & 1][0]; pw.y &= pmk[it & 1][1]; pw.z &= pmk[it & 1][2]; pw.w &= pmk[it & 1][3]; }
;                           Ot[it] = __builtin_amdgcn_mfma_f32_16x16x32_bf16(Vf[ks], __builtin_bit_cast(bf16x8, pw), Ot[it], 0, 0, 0);
;                           __builtin_amdgcn_sched_group_barrier(0x100, 1, 0); __builtin_amdgcn_sched_group_barrier(0x8, 1, 0); }); }
.LBB0_988:
	v_lshl_add_u64 v[152:153], s[64:65], 0, v[148:149]
	s_mov_b32 s12, 0x10800000
	v_add_co_u32_e32 v72, vcc, s12, v152
	v_mov_b32_e32 v192, v161
	v_mov_b32_e32 v74, v162
	v_lshl_add_u64 v[150:151], s[62:63], 0, v[148:149]
	v_addc_co_u32_e32 v73, vcc, 0, v153, vcc
	s_mov_b32 s12, 0x4a900000
	global_load_dwordx4 v[96:99], v[72:73], off offset:256
	v_add_co_u32_e32 v72, vcc, s12, v150
	s_mov_b32 s12, 0x10840000
	s_nop 0
	v_addc_co_u32_e32 v73, vcc, 0, v151, vcc
	global_load_dwordx4 v[100:103], v[72:73], off offset:256
	v_add_co_u32_e32 v72, vcc, s12, v152
	s_mov_b32 s12, 0x4a940000
	s_nop 0
	v_addc_co_u32_e32 v73, vcc, 0, v153, vcc
	global_load_dwordx4 v[104:107], v[72:73], off offset:256
	v_add_co_u32_e32 v72, vcc, s12, v150
	s_waitcnt vmcnt(14)
	ds_write_b128 v214, v[64:67] offset:16384
	v_addc_co_u32_e32 v73, vcc, 0, v151, vcc
	global_load_dwordx4 v[108:111], v[72:73], off offset:256
	v_lshlrev_b32_e32 v72, 3, v74
	s_waitcnt vmcnt(14)
	ds_write_b128 v214, v[68:71] offset:49152
	s_waitcnt vmcnt(13)
	ds_write_b128 v214, v[76:79] offset:24576
	s_waitcnt vmcnt(12)
	ds_write_b128 v214, v[84:87] offset:57344
	v_add_u32_e32 v64, v175, v168
	v_add_u32_e32 v65, v169, v168
	v_sub_u32_e32 v112, 0x7f, v72
	ds_read_b64_tr_b16 v[72:73], v64
	ds_read_b64_tr_b16 v[80:81], v64 offset:8192
	ds_read_b64_tr_b16 v[88:89], v64 offset:16384
	ds_read_b64_tr_b16 v[92:93], v64 offset:24576
	ds_read_b64_tr_b16 v[74:75], v65 offset:1024
	ds_read_b64_tr_b16 v[82:83], v65 offset:9216
	ds_read_b64_tr_b16 v[90:91], v65 offset:17408
	ds_read_b64_tr_b16 v[94:95], v65 offset:25600
	v_cvt_f32_i32_e32 v124, v112
	s_add_i32 s43, s44, 1
	s_cmp_lt_u32 s43, s73
	s_cselect_b64 s[22:23], -1, 0
	s_cmp_ge_u32 s43, s73
	v_add_u32_e32 v125, v170, v171
	ds_read_b128 v[64:67], v125
	ds_read_b128 v[76:79], v125 offset:4096
	v_add_u32_e32 v126, v170, v172
	v_add_u32_e32 v127, v170, v173
	v_add_u32_e32 v140, v170, v174
	s_waitcnt lgkmcnt(1)
	v_and_b32_e32 v64, v64, v205
	v_and_b32_e32 v65, v65, v206
	v_and_b32_e32 v66, v66, v207
	v_and_b32_e32 v67, v67, v208
	s_nop 1
	v_mfma_f32_16x16x32_bf16 v[68:71], v[72:75], v[64:67], 0
	ds_read_b128 v[84:87], v125 offset:8192
	s_waitcnt lgkmcnt(1)
	v_and_b32_e32 v64, v76, v209
	v_and_b32_e32 v65, v77, v210
	v_and_b32_e32 v66, v78, v211
	v_and_b32_e32 v67, v79, v212
	s_nop 1
	v_mfma_f32_16x16x32_bf16 v[64:67], v[72:75], v[64:67], 0
	ds_read_b128 v[76:79], v126 offset:8192
	s_waitcnt lgkmcnt(0)
	v_and_b32_e32 v76, v76, v205
	v_mfma_f32_16x16x32_bf16 v[84:87], v[72:75], v[84:87], 0
	ds_read_b128 v[112:115], v125 offset:12288
	v_and_b32_e32 v77, v77, v206
	v_and_b32_e32 v78, v78, v207
	v_and_b32_e32 v79, v79, v208
	s_nop 1
	v_mfma_f32_16x16x32_bf16 v[76:79], v[80:83], v[76:79], v[84:87]
	s_nop 2
	ds_read_b128 v[84:87], v126 offset:12288
	s_waitcnt lgkmcnt(1)
	v_mfma_f32_16x16x32_bf16 v[112:115], v[72:75], v[112:115], 0
	ds_read_b128 v[116:119], v125 offset:16384
	s_waitcnt lgkmcnt(1)
	v_and_b32_e32 v84, v84, v209
	v_and_b32_e32 v85, v85, v210
	v_and_b32_e32 v86, v86, v211
	v_and_b32_e32 v87, v87, v212
	s_nop 1
	v_mfma_f32_16x16x32_bf16 v[84:87], v[80:83], v[84:87], v[112:115]
	s_nop 2
	ds_read_b128 v[112:115], v126 offset:16384
	s_waitcnt lgkmcnt(1)
	v_mfma_f32_16x16x32_bf16 v[116:119], v[72:75], v[116:119], 0
	ds_read_b128 v[120:123], v127 offset:16384
	s_waitcnt lgkmcnt(0)
	v_and_b32_e32 v120, v120, v205
	v_mfma_f32_16x16x32_bf16 v[112:115], v[80:83], v[112:115], v[116:119]
	v_and_b32_e32 v121, v121, v206
	v_and_b32_e32 v122, v122, v207
	v_and_b32_e32 v123, v123, v208
	s_nop 0
	ds_read_b128 v[116:119], v125 offset:20480
	v_mfma_f32_16x16x32_bf16 v[128:131], v[88:91], v[120:123], v[112:115]
	s_nop 2
	ds_read_b128 v[112:115], v126 offset:20480
	s_waitcnt lgkmcnt(1)
	v_mfma_f32_16x16x32_bf16 v[116:119], v[72:75], v[116:119], 0
	ds_read_b128 v[120:123], v127 offset:20480
	s_waitcnt lgkmcnt(0)
	v_and_b32_e32 v120, v120, v209
	v_mfma_f32_16x16x32_bf16 v[112:115], v[80:83], v[112:115], v[116:119]
	v_and_b32_e32 v121, v121, v210
	v_and_b32_e32 v122, v122, v211
	v_and_b32_e32 v123, v123, v212
	s_nop 0
	ds_read_b128 v[116:119], v125 offset:24576
	v_mfma_f32_16x16x32_bf16 v[132:135], v[88:91], v[120:123], v[112:115]
	s_nop 2
	ds_read_b128 v[112:115], v126 offset:24576
	s_waitcnt lgkmcnt(1)
	v_mfma_f32_16x16x32_bf16 v[116:119], v[72:75], v[116:119], 0
	ds_read_b128 v[120:123], v127 offset:24576
	s_waitcnt lgkmcnt(1)
	v_mfma_f32_16x16x32_bf16 v[112:115], v[80:83], v[112:115], v[116:119]
	s_nop 4
	ds_read_b128 v[116:119], v140 offset:24576
	s_waitcnt lgkmcnt(1)
	v_mfma_f32_16x16x32_bf16 v[112:115], v[88:91], v[120:123], v[112:115]
	ds_read_b128 v[120:123], v125 offset:28672
	s_waitcnt lgkmcnt(1)
	v_and_b32_e32 v116, v116, v205
	v_and_b32_e32 v117, v117, v206
	v_and_b32_e32 v118, v118, v207
	v_and_b32_e32 v119, v119, v208
	s_nop 1
	v_mfma_f32_16x16x32_bf16 v[136:139], v[92:95], v[116:119], v[112:115]
	s_nop 2
	ds_read_b128 v[112:115], v126 offset:28672
	s_waitcnt lgkmcnt(1)
	v_mfma_f32_16x16x32_bf16 v[116:119], v[72:75], v[120:123], 0
	ds_read_b128 v[120:123], v127 offset:28672
	s_waitcnt lgkmcnt(1)
	v_mfma_f32_16x16x32_bf16 v[112:115], v[80:83], v[112:115], v[116:119]
	s_nop 4
	ds_read_b128 v[116:119], v140 offset:28672
	s_waitcnt lgkmcnt(1)
	v_mfma_f32_16x16x32_bf16 v[112:115], v[88:91], v[120:123], v[112:115]
	s_waitcnt lgkmcnt(0)
; __device__ __forceinline__ unsigned cvt_pk_bf16(float lo, float hi) { unsigned r; asm volatile("v_cvt_pk_bf16_f32 %0, %1, %2" : "=v"(r) : "v"(lo), "v"(hi)); return r; }
; __device__ __forceinline__ float bf_lo(unsigned w) { return __uint_as_float(w << 16); }
; __device__ __forceinline__ float bf_hi(unsigned w) { return __uint_as_float(w & 0xffff0000u); }
; #define SCAN_QREAD(b_, it_) do { _Pragma("unroll") for (int ks = 0; ks < 2; ++ks) { const int qo = ((p & 1) ? LQ1 : LQ0) + 16 * (it_) * QS; \
;                         const u32x2 lo = *(const volatile LAS u32x2*)(bQs[ks][0] + qo), hi = *(const volatile LAS u32x2*)(bQs[ks][1] + qo);     qf[b_][ks] = (u32x4){lo.x, lo.y, hi.x, hi.y}; } } while (0)
; __device__ __forceinline__ void scan_phase(const Frame& F, const bf16_t* Q, const bf16_t* K, const bf16_t* V, const bf16_t* PB, bf16_t* OF, bf16_t* OB, int half) {
;     ...
;                     { float fk = __builtin_amdgcn_exp2f(lg2 * (float)(dir ? 8 * quad_l : 127 - 8 * quad_l));
; #pragma unroll
;                       for (int ks = 0; ks < 4; ++ks) { u32x4 vw = __builtin_bit_cast(u32x4, Vf[ks]); float f = fk;
; #pragma unroll
;                         for (int e2 = 0; e2 < 4; ++e2) { const float f0 = f, f1 = f * gm1; f = f1 * gm1;
;                             vw[e2] = cvt_pk_bf16(bf_lo(vw[e2]) * f0, bf_hi(vw[e2]) * f1); }
;                         Vf[ks] = __builtin_bit_cast(bf16x8, vw); fk *= gm32; } }
;                 }
;                 __builtin_amdgcn_sched_barrier(0);
;                 {
;                     bf16x8 Rf[2];
; #pragma unroll
;                     for (int ks = 0; ks < 2; ++ks) { const f32x4 r0v = Rt[4 * p + 2 * ks], r1v = Rt[4 * p + 2 * ks + 1];
;                         const u32x4 wvv = {cvt_pk_bf16(r0v[0], r0v[1]), cvt_pk_bf16(r0v[2], r0v[3]), cvt_pk_bf16(r1v[0], r1v[1]), cvt_pk_bf16(r1v[2], r1v[3])};
;                         Rf[ks] = __builtin_bit_cast(bf16x8, wvv); }
;                     u32x4 qf[2][2];
;     ...
;                     SCAN_QREAD(0, 0);
; #pragma unroll
;                     for (int it = 0; it < 8; ++it) { if (it < 7) SCAN_QREAD((it + 1) & 1, it + 1);
; #pragma unroll
;                         for (int ks = 0; ks < 2; ++ks) Ot[it] = __builtin_amdgcn_mfma_f32_16x16x32_bf16(Rf[ks], __builtin_bit_cast(bf16x8, qf[it & 1][ks]), Ot[it], 0, 0, 0); }
	v_and_b32_e32 v116, v116, v209
	v_and_b32_e32 v117, v117, v210
	v_and_b32_e32 v118, v118, v211
	v_and_b32_e32 v119, v119, v212
	s_nop 1
	v_mfma_f32_16x16x32_bf16 v[140:143], v[92:95], v[116:119], v[112:115]
	s_nop 2
	v_mul_f32_e32 v112, s54, v124
	v_exp_f32_e32 v112, v112
	v_lshlrev_b32_e32 v113, 16, v72
	v_and_b32_e32 v72, 0xffff0000, v72
	v_lshlrev_b32_e32 v116, 16, v73
	v_mul_f32_e32 v114, s18, v112
	v_mul_f32_e32 v113, v112, v113
	v_mul_f32_e32 v115, s18, v114
	v_mul_f32_e32 v72, v114, v72
	v_cvt_pk_bf16_f32 v72, v113, v72
	v_mul_f32_e32 v113, s18, v115
	v_mul_f32_e32 v114, s18, v113
	v_and_b32_e32 v73, 0xffff0000, v73
	v_mul_f32_e32 v115, v115, v116
	v_mul_f32_e32 v73, v113, v73
	v_mul_f32_e32 v113, s18, v114
	v_lshlrev_b32_e32 v116, 16, v74
	v_and_b32_e32 v74, 0xffff0000, v74
	v_cvt_pk_bf16_f32 v73, v115, v73
	v_mul_f32_e32 v115, s18, v113
	v_mul_f32_e32 v114, v114, v116
	v_mul_f32_e32 v74, v113, v74
	v_cvt_pk_bf16_f32 v74, v114, v74
	v_mul_f32_e32 v113, s18, v115
	v_lshlrev_b32_e32 v114, 16, v75
	v_and_b32_e32 v75, 0xffff0000, v75
	v_mul_f32_e32 v112, s36, v112
	v_mul_f32_e32 v114, v115, v114
	v_mul_f32_e32 v75, v113, v75
	v_mul_f32_e32 v113, s18, v112
	v_cvt_pk_bf16_f32 v75, v114, v75
	v_mul_f32_e32 v114, s18, v113
	v_lshlrev_b32_e32 v115, 16, v80
	v_and_b32_e32 v80, 0xffff0000, v80
	v_mul_f32_e32 v115, v112, v115
	v_mul_f32_e32 v80, v113, v80
	v_mul_f32_e32 v113, s18, v114
	v_cvt_pk_bf16_f32 v80, v115, v80
	v_mul_f32_e32 v115, s18, v113
	v_lshlrev_b32_e32 v116, 16, v81
	v_and_b32_e32 v81, 0xffff0000, v81
	v_mul_f32_e32 v114, v114, v116
	v_mul_f32_e32 v81, v113, v81
	v_mul_f32_e32 v113, s18, v115
	v_lshlrev_b32_e32 v116, 16, v82
	v_and_b32_e32 v82, 0xffff0000, v82
	v_cvt_pk_bf16_f32 v81, v114, v81
	v_mul_f32_e32 v114, s18, v113
	v_mul_f32_e32 v115, v115, v116
	v_mul_f32_e32 v82, v113, v82
	v_cvt_pk_bf16_f32 v82, v115, v82
	v_mul_f32_e32 v113, s18, v114
	v_lshlrev_b32_e32 v115, 16, v83
	v_and_b32_e32 v83, 0xffff0000, v83
	v_mul_f32_e32 v112, s36, v112
	v_mul_f32_e32 v114, v114, v115
	v_mul_f32_e32 v83, v113, v83
	v_mul_f32_e32 v113, s18, v112
	v_cvt_pk_bf16_f32 v83, v114, v83
	v_mul_f32_e32 v114, s18, v113
	v_lshlrev_b32_e32 v115, 16, v88
	v_and_b32_e32 v88, 0xffff0000, v88
	v_mul_f32_e32 v115, v112, v115
	v_mul_f32_e32 v88, v113, v88
	v_mul_f32_e32 v113, s18, v114
	v_cvt_pk_bf16_f32 v88, v115, v88
	v_mul_f32_e32 v115, s18, v113
	v_lshlrev_b32_e32 v116, 16, v89
	v_and_b32_e32 v89, 0xffff0000, v89
	v_mul_f32_e32 v114, v114, v116
	v_mul_f32_e32 v89, v113, v89
	v_mul_f32_e32 v113, s18, v115
	v_lshlrev_b32_e32 v116, 16, v90
	v_and_b32_e32 v90, 0xffff0000, v90
	v_cvt_pk_bf16_f32 v89, v114, v89
	v_mul_f32_e32 v114, s18, v113
	v_mul_f32_e32 v115, v115, v116
	v_mul_f32_e32 v90, v113, v90
	v_cvt_pk_bf16_f32 v90, v115, v90
	v_mul_f32_e32 v113, s18, v114
	v_lshlrev_b32_e32 v115, 16, v91
	v_and_b32_e32 v91, 0xffff0000, v91
	v_mul_f32_e32 v112, s36, v112
	v_mul_f32_e32 v114, v114, v115
	v_mul_f32_e32 v91, v113, v91
	v_mul_f32_e32 v113, s18, v112
	v_lshlrev_b32_e32 v115, 16, v92
	v_and_b32_e32 v92, 0xffff0000, v92
	v_cvt_pk_bf16_f32 v91, v114, v91
	v_mul_f32_e32 v114, s18, v113
	v_mul_f32_e32 v112, v112, v115
	v_mul_f32_e32 v92, v113, v92
	v_cvt_pk_bf16_f32 v92, v112, v92
	v_mul_f32_e32 v112, s18, v114
	v_mul_f32_e32 v113, s18, v112
	v_lshlrev_b32_e32 v115, 16, v93
	v_and_b32_e32 v93, 0xffff0000, v93
	v_mul_f32_e32 v114, v114, v115
	v_mul_f32_e32 v93, v112, v93
	v_mul_f32_e32 v112, s18, v113
	v_lshlrev_b32_e32 v115, 16, v94
	v_and_b32_e32 v94, 0xffff0000, v94
	v_cvt_pk_bf16_f32 v93, v114, v93
	v_mul_f32_e32 v114, s18, v112
	v_mul_f32_e32 v113, v113, v115
	v_mul_f32_e32 v94, v112, v94
	v_cvt_pk_bf16_f32 v94, v113, v94
	v_mul_f32_e32 v112, s18, v114
	v_lshlrev_b32_e32 v113, 16, v95
	v_and_b32_e32 v95, 0xffff0000, v95
	v_mul_f32_e32 v113, v114, v113
	v_mul_f32_e32 v95, v112, v95
	v_cvt_pk_bf16_f32 v95, v113, v95
	v_add_u32_e32 v217, v163, v164
	v_add_u32_e32 v218, v163, v165
	v_cvt_pk_bf16_f32 v194, v44, v45
	v_cvt_pk_bf16_f32 v195, v46, v47
	v_cvt_pk_bf16_f32 v196, v40, v41
	v_cvt_pk_bf16_f32 v197, v42, v43
	v_cvt_pk_bf16_f32 v222, v36, v37
	v_cvt_pk_bf16_f32 v223, v38, v39
	v_cvt_pk_bf16_f32 v224, v32, v33
	v_cvt_pk_bf16_f32 v225, v34, v35
	ds_read_b64 v[112:113], v217
	ds_read_b64 v[114:115], v218
	v_add_u32_e32 v219, v163, v166
	v_add_u32_e32 v220, v163, v167
	ds_read_b64 v[116:117], v219
	ds_read_b64 v[118:119], v220
	ds_read_b64 v[120:121], v217 offset:2048
	ds_read_b64 v[122:123], v218 offset:2048
	ds_read_b64 v[124:125], v219 offset:2048
	ds_read_b64 v[126:127], v220 offset:2048
	s_waitcnt lgkmcnt(6)
	v_mfma_f32_16x16x32_bf16 v[68:71], v[194:197], v[112:115], v[68:71]
	s_waitcnt lgkmcnt(4)
	v_mfma_f32_16x16x32_bf16 v[112:115], v[222:225], v[116:119], v[68:71]
	s_nop 5
	ds_read_b64 v[68:69], v217 offset:4096
	ds_read_b64 v[70:71], v218 offset:4096
	ds_read_b64 v[226:227], v219 offset:4096
	ds_read_b64 v[228:229], v220 offset:4096
	s_waitcnt lgkmcnt(6)
	v_mfma_f32_16x16x32_bf16 v[64:67], v[194:197], v[120:123], v[64:67]
	s_waitcnt lgkmcnt(4)
	v_mfma_f32_16x16x32_bf16 v[116:119], v[222:225], v[124:127], v[64:67]
	s_nop 5
	ds_read_b64 v[64:65], v217 offset:6144
	ds_read_b64 v[66:67], v218 offset:6144
	ds_read_b64 v[124:125], v219 offset:6144
	ds_read_b64 v[126:127], v220 offset:6144
	s_waitcnt lgkmcnt(6)
	v_mfma_f32_16x16x32_bf16 v[68:71], v[194:197], v[68:71], v[76:79]
	s_waitcnt lgkmcnt(4)
	v_mfma_f32_16x16x32_bf16 v[120:123], v[222:225], v[226:229], v[68:71]
	s_nop 5
	ds_read_b64 v[68:69], v217 offset:8192
	ds_read_b64 v[70:71], v218 offset:8192
	ds_read_b64 v[76:77], v219 offset:8192
	ds_read_b64 v[78:79], v220 offset:8192
	s_waitcnt lgkmcnt(6)
; __device__ __forceinline__ void scan_phase(const Frame& F, const bf16_t* Q, const bf16_t* K, const bf16_t* V, const bf16_t* PB, bf16_t* OF, bf16_t* OB, int half) {
;     ...
;                     for (int ks = 0; ks < 2; ++ks) { const f32x4 r0v = Rt[4 * p + 2 * ks], r1v = Rt[4 * p + 2 * ks + 1];
;                         const u32x4 wvv = {cvt_pk_bf16(r0v[0], r0v[1]), cvt_pk_bf16(r0v[2], r0v[3]), cvt_pk_bf16(r1v[0], r1v[1]), cvt_pk_bf16(r1v[2], r1v[3])};
;                         Rf[ks] = __builtin_bit_cast(bf16x8, wvv); }
;                     u32x4 qf[2][2];
;     ...
;                     SCAN_QREAD(0, 0);
; #pragma unroll
;                     for (int it = 0; it < 8; ++it) { if (it < 7) SCAN_QREAD((it + 1) & 1, it + 1);
; #pragma unroll
;                         for (int ks = 0; ks < 2; ++ks) Ot[it] = __builtin_amdgcn_mfma_f32_16x16x32_bf16(Rf[ks], __builtin_bit_cast(bf16x8, qf[it & 1][ks]), Ot[it], 0, 0, 0); }
;     ...
;                     __builtin_amdgcn_sched_group_barrier(0x100, 4, 0);
;                     __builtin_amdgcn_sched_group_barrier(0x100, 4, 0); __builtin_amdgcn_sched_group_barrier(0x8, 2, 0);
;                     __builtin_amdgcn_sched_group_barrier(0x100, 4, 0); __builtin_amdgcn_sched_group_barrier(0x8, 2, 0);
;                     __builtin_amdgcn_sched_group_barrier(0x100, 4, 0); __builtin_amdgcn_sched_group_barrier(0x8, 2, 0);
;                     __builtin_amdgcn_sched_group_barrier(0x100, 4, 0); __builtin_amdgcn_sched_group_barrier(0x8, 2, 0);
;                     __builtin_amdgcn_sched_group_barrier(0x100, 4, 0); __builtin_amdgcn_sched_group_barrier(0x8, 2, 0);
;                     __builtin_amdgcn_sched_group_barrier(0x100, 4, 0); __builtin_amdgcn_sched_group_barrier(0x8, 2, 0);
;                     __builtin_amdgcn_sched_group_barrier(0x100, 4, 0); __builtin_amdgcn_sched_group_barrier(0x8, 2, 0);
;                     __builtin_amdgcn_sched_group_barrier(0x8, 2, 0);
;                 }
;                 __builtin_amdgcn_sched_barrier(0);
;                 { s16x4 kl[2][4], kh[2][4];
;     ...
;                 SCAN_KREAD(0, 0);
; #pragma unroll
;                 for (int mt = 0; mt < 4; ++mt) { if (mt < 3) SCAN_KREAD((mt + 1) & 1, mt + 1);
;                     f32x4 acc = Rt[4 * p + mt] * c1;
; #pragma unroll
	v_mfma_f32_16x16x32_bf16 v[64:67], v[194:197], v[64:67], v[84:87]
	s_waitcnt lgkmcnt(4)
	v_mfma_f32_16x16x32_bf16 v[124:127], v[222:225], v[124:127], v[64:67]
	s_nop 5
	ds_read_b64 v[64:65], v217 offset:10240
	ds_read_b64 v[66:67], v218 offset:10240
	ds_read_b64 v[84:85], v219 offset:10240
	ds_read_b64 v[86:87], v220 offset:10240
	s_waitcnt lgkmcnt(6)
	v_mfma_f32_16x16x32_bf16 v[68:71], v[194:197], v[68:71], v[128:131]
	s_waitcnt lgkmcnt(4)
	v_mfma_f32_16x16x32_bf16 v[128:131], v[222:225], v[76:79], v[68:71]
	s_nop 5
	ds_read_b64 v[68:69], v217 offset:12288
	ds_read_b64 v[70:71], v218 offset:12288
	ds_read_b64 v[76:77], v219 offset:12288
	ds_read_b64 v[78:79], v220 offset:12288
	s_waitcnt lgkmcnt(6)
	v_mfma_f32_16x16x32_bf16 v[64:67], v[194:197], v[64:67], v[132:135]
	s_waitcnt lgkmcnt(4)
	v_mfma_f32_16x16x32_bf16 v[132:135], v[222:225], v[84:87], v[64:67]
	s_nop 5
	ds_read_b64 v[64:65], v217 offset:14336
	ds_read_b64 v[66:67], v218 offset:14336
	ds_read_b64 v[84:85], v219 offset:14336
	ds_read_b64 v[86:87], v220 offset:14336
	s_waitcnt lgkmcnt(6)
	v_mfma_f32_16x16x32_bf16 v[68:71], v[194:197], v[68:71], v[136:139]
	s_waitcnt lgkmcnt(4)
	v_mfma_f32_16x16x32_bf16 v[136:139], v[222:225], v[76:79], v[68:71]
	s_waitcnt lgkmcnt(2)
	v_mfma_f32_16x16x32_bf16 v[64:67], v[194:197], v[64:67], v[140:143]
	s_waitcnt lgkmcnt(0)
	v_mfma_f32_16x16x32_bf16 v[140:143], v[222:225], v[84:87], v[64:67]
	v_add_u32_e32 v221, v182, v189
	v_add_u32_e32 v222, v182, v190
	s_nop 3
	ds_read_b64_tr_b16 v[64:65], v221 offset:32768
	ds_read_b64_tr_b16 v[66:67], v222 offset:33280
	ds_read_b64_tr_b16 v[68:69], v221 offset:36864
	ds_read_b64_tr_b16 v[70:71], v222 offset:37376
	v_mov_b32_e32 v145, v144
	ds_read_b64_tr_b16 v[76:77], v221 offset:40960
	ds_read_b64_tr_b16 v[78:79], v222 offset:41472
	v_add_u32_e32 v223, v182, v187
	v_add_u32_e32 v224, v182, v188
	v_mul_f32_e32 v46, v144, v46
	v_mul_f32_e32 v47, v145, v47
	v_mul_f32_e32 v44, v146, v44
	v_mul_f32_e32 v45, v147, v45
	ds_read_b64_tr_b16 v[84:85], v221 offset:45056
	ds_read_b64_tr_b16 v[86:87], v222 offset:45568
	ds_read_b64_tr_b16 v[194:195], v223 offset:32768
	ds_read_b64_tr_b16 v[196:197], v224 offset:33280
	ds_read_b64_tr_b16 v[228:229], v223 offset:36864
	ds_read_b64_tr_b16 v[230:231], v224 offset:37376
	ds_read_b64_tr_b16 v[232:233], v223 offset:40960
	ds_read_b64_tr_b16 v[234:235], v224 offset:41472
	ds_read_b64_tr_b16 v[236:237], v223 offset:45056
	ds_read_b64_tr_b16 v[238:239], v224 offset:45568
	s_waitcnt lgkmcnt(14)
	v_mfma_f32_16x16x32_bf16 v[44:47], v[64:67], v[72:75], v[44:47]
	v_add_u32_e32 v225, v182, v185
	v_add_u32_e32 v226, v182, v186
	v_mul_f32_e32 v42, v144, v42
	v_mul_f32_e32 v43, v145, v43
	s_waitcnt lgkmcnt(12)
	v_mfma_f32_16x16x32_bf16 v[44:47], v[68:71], v[80:83], v[44:47]
	v_mul_f32_e32 v40, v146, v40
	v_mul_f32_e32 v41, v147, v41
	v_add_u32_e32 v227, v182, v183
	v_mul_f32_e32 v38, v144, v38
	v_mul_f32_e32 v39, v145, v39
	s_waitcnt lgkmcnt(10)
	v_mfma_f32_16x16x32_bf16 v[44:47], v[76:79], v[88:91], v[44:47]
	v_mul_f32_e32 v36, v146, v36
	v_mul_f32_e32 v37, v147, v37
	v_mul_f32_e32 v34, v144, v34
	v_mul_f32_e32 v35, v145, v35
	v_mul_f32_e32 v32, v146, v32
	v_mul_f32_e32 v33, v147, v33
	s_waitcnt lgkmcnt(8)
	v_mfma_f32_16x16x32_bf16 v[44:47], v[84:87], v[92:95], v[44:47]
	ds_read_b64_tr_b16 v[64:65], v225 offset:32768
	ds_read_b64_tr_b16 v[66:67], v226 offset:33280
	ds_read_b64_tr_b16 v[68:69], v225 offset:36864
	ds_read_b64_tr_b16 v[70:71], v226 offset:37376
	ds_read_b64_tr_b16 v[76:77], v225 offset:40960
	ds_read_b64_tr_b16 v[78:79], v226 offset:41472
	ds_read_b64_tr_b16 v[84:85], v225 offset:45056
	ds_read_b64_tr_b16 v[86:87], v226 offset:45568
	s_waitcnt lgkmcnt(14)
	v_mfma_f32_16x16x32_bf16 v[40:43], v[194:197], v[72:75], v[40:43]
	s_waitcnt lgkmcnt(12)
	v_mfma_f32_16x16x32_bf16 v[40:43], v[228:231], v[80:83], v[40:43]
	v_add_u32_e32 v228, v182, v184
	s_waitcnt lgkmcnt(10)
	v_mfma_f32_16x16x32_bf16 v[40:43], v[232:235], v[88:91], v[40:43]
	s_waitcnt lgkmcnt(8)
	v_mfma_f32_16x16x32_bf16 v[40:43], v[236:239], v[92:95], v[40:43]
	ds_read_b64_tr_b16 v[194:195], v227 offset:32768
	ds_read_b64_tr_b16 v[196:197], v228 offset:33280
	ds_read_b64_tr_b16 v[230:231], v227 offset:36864
	ds_read_b64_tr_b16 v[232:233], v228 offset:37376
	ds_read_b64_tr_b16 v[234:235], v227 offset:40960
	ds_read_b64_tr_b16 v[236:237], v228 offset:41472
	ds_read_b64_tr_b16 v[238:239], v227 offset:45056
	ds_read_b64_tr_b16 v[240:241], v228 offset:45568
	s_waitcnt lgkmcnt(14)
	v_mfma_f32_16x16x32_bf16 v[36:39], v[64:67], v[72:75], v[36:39]
	s_waitcnt lgkmcnt(0)
	s_barrier
	s_waitcnt vmcnt(3)
	ds_write_b128 v214, v[96:99]
	s_waitcnt vmcnt(2)
	ds_write_b128 v214, v[100:103] offset:32768
	s_waitcnt lgkmcnt(14)
	v_mfma_f32_16x16x32_bf16 v[36:39], v[68:71], v[80:83], v[36:39]
	s_waitcnt vmcnt(1)
	ds_write_b128 v214, v[104:107] offset:8192
	s_waitcnt vmcnt(0)
	ds_write_b128 v214, v[108:111] offset:40960
	s_waitcnt lgkmcnt(14)
	v_mfma_f32_16x16x32_bf16 v[36:39], v[76:79], v[88:91], v[36:39]
	s_waitcnt lgkmcnt(12)
	v_mfma_f32_16x16x32_bf16 v[36:39], v[84:87], v[92:95], v[36:39]
	s_waitcnt lgkmcnt(10)
	v_mfma_f32_16x16x32_bf16 v[32:35], v[194:197], v[72:75], v[32:35]
	s_waitcnt lgkmcnt(8)
	v_mfma_f32_16x16x32_bf16 v[32:35], v[230:233], v[80:83], v[32:35]
	s_waitcnt lgkmcnt(6)
	v_mfma_f32_16x16x32_bf16 v[32:35], v[234:237], v[88:91], v[32:35]
	s_waitcnt lgkmcnt(4)
	v_mfma_f32_16x16x32_bf16 v[32:35], v[238:241], v[92:95], v[32:35]
	v_add_co_u32_e32 v64, vcc, 0x10800000, v152
	s_nop 1
	v_addc_co_u32_e32 v65, vcc, 0, v153, vcc
	v_add_co_u32_e32 v68, vcc, 0x4a900000, v150
	global_load_dwordx4 v[64:67], v[64:65], off offset:384
	s_nop 0
	v_addc_co_u32_e32 v69, vcc, 0, v151, vcc
	v_add_co_u32_e32 v76, vcc, 0x10840000, v152
	global_load_dwordx4 v[68:71], v[68:69], off offset:384
	s_nop 0
	v_addc_co_u32_e32 v77, vcc, 0, v153, vcc
	v_add_co_u32_e32 v84, vcc, 0x4a940000, v150
	global_load_dwordx4 v[76:79], v[76:77], off offset:384
	s_nop 0
	v_addc_co_u32_e32 v85, vcc, 0, v151, vcc
	global_load_dwordx4 v[84:87], v[84:85], off offset:384
	s_cbranch_scc1 .LBB0_990
	s_add_i32 s12, s40, s44
	s_ashr_i32 s13, s12, 31
	s_lshl_b64 s[12:13], s[12:13], 18
	s_add_u32 s12, s38, s12
	s_mov_b32 s34, m0
	s_mov_b32 m0, s74
	s_nop 0
	global_load_lds_dwordx4 v154, s[30:31]
	s_mov_b32 m0, s34
	s_addc_u32 s13, s39, s13
	s_mov_b32 s34, m0
	s_mov_b32 m0, s75
	s_nop 0
	global_load_lds_dwordx4 v155, s[12:13]
	s_mov_b32 m0, s34
	s_nop 0
	s_mov_b32 s34, m0
	s_mov_b32 m0, s79
	s_nop 0
	global_load_lds_dwordx4 v156, s[30:31]
	s_mov_b32 m0, s34
	s_nop 0
	s_mov_b32 s34, m0
	s_mov_b32 m0, s80
	s_nop 0
	global_load_lds_dwordx4 v157, s[12:13]
	s_mov_b32 m0, s34
	s_nop 0
	s_mov_b32 s34, m0
	s_mov_b32 m0, s81
	s_nop 0
	global_load_lds_dwordx4 v158, s[30:31]
	s_mov_b32 m0, s34
	s_nop 0
	s_mov_b32 s34, m0
	s_mov_b32 m0, s82
	s_nop 0
	global_load_lds_dwordx4 v159, s[12:13]
	s_mov_b32 m0, s34
	s_nop 0
	s_mov_b32 s34, m0
	s_mov_b32 m0, s83
	s_nop 0
	global_load_lds_dwordx4 v215, s[30:31]
	s_mov_b32 m0, s34
	s_nop 0
	s_mov_b32 s34, m0
	s_mov_b32 m0, s84
	s_nop 0
	global_load_lds_dwordx4 v216, s[12:13]
	s_mov_b32 m0, s34
; __device__ __forceinline__ void scan_phase(const Frame& F, const bf16_t* Q, const bf16_t* K, const bf16_t* V, const bf16_t* PB, bf16_t* OF, bf16_t* OB, int half) {
;     ...
;                 {
;                     bf16x8 Rf[2];
; #pragma unroll
;                     for (int ks = 0; ks < 2; ++ks) { const f32x4 r0v = Rt[4 * p + 2 * ks], r1v = Rt[4 * p + 2 * ks + 1];
;                         const u32x4 wvv = {cvt_pk_bf16(r0v[0], r0v[1]), cvt_pk_bf16(r0v[2], r0v[3]), cvt_pk_bf16(r1v[0], r1v[1]), cvt_pk_bf16(r1v[2], r1v[3])};
;                         Rf[ks] = __builtin_bit_cast(bf16x8, wvv); }
;                     u32x4 qf[2][2];
;     ...
;                     SCAN_QREAD(0, 0);
; #pragma unroll
;                     for (int it = 0; it < 8; ++it) { if (it < 7) SCAN_QREAD((it + 1) & 1, it + 1);
; #pragma unroll
;                         for (int ks = 0; ks < 2; ++ks) Ot[it] = __builtin_amdgcn_mfma_f32_16x16x32_bf16(Rf[ks], __builtin_bit_cast(bf16x8, qf[it & 1][ks]), Ot[it], 0, 0, 0); }
;     ...
;                     __builtin_amdgcn_sched_group_barrier(0x100, 4, 0);
;                     __builtin_amdgcn_sched_group_barrier(0x100, 4, 0); __builtin_amdgcn_sched_group_barrier(0x8, 2, 0);
;                     __builtin_amdgcn_sched_group_barrier(0x100, 4, 0); __builtin_amdgcn_sched_group_barrier(0x8, 2, 0);
;                     __builtin_amdgcn_sched_group_barrier(0x100, 4, 0); __builtin_amdgcn_sched_group_barrier(0x8, 2, 0);
;                     __builtin_amdgcn_sched_group_barrier(0x100, 4, 0); __builtin_amdgcn_sched_group_barrier(0x8, 2, 0);
;                     __builtin_amdgcn_sched_group_barrier(0x100, 4, 0); __builtin_amdgcn_sched_group_barrier(0x8, 2, 0);
;                     __builtin_amdgcn_sched_group_barrier(0x100, 4, 0); __builtin_amdgcn_sched_group_barrier(0x8, 2, 0);
;                     __builtin_amdgcn_sched_group_barrier(0x100, 4, 0); __builtin_amdgcn_sched_group_barrier(0x8, 2, 0);
;                     __builtin_amdgcn_sched_group_barrier(0x8, 2, 0);
;                 }
;                 __builtin_amdgcn_sched_barrier(0);
;                 { s16x4 kl[2][4], kh[2][4];
;     ...
;                 SCAN_KREAD(0, 0);
; #pragma unroll
;                 for (int mt = 0; mt < 4; ++mt) { if (mt < 3) SCAN_KREAD((mt + 1) & 1, mt + 1);
;                     f32x4 acc = Rt[4 * p + mt] * c1;
; #pragma unroll
.LBB0_990:
	v_cvt_pk_bf16_f32 v194, v28, v29
	v_cvt_pk_bf16_f32 v195, v30, v31
	v_cvt_pk_bf16_f32 v196, v20, v21
	v_cvt_pk_bf16_f32 v197, v22, v23
	v_cvt_pk_bf16_f32 v230, v16, v17
	v_cvt_pk_bf16_f32 v231, v18, v19
	v_cvt_pk_bf16_f32 v232, v24, v25
	v_cvt_pk_bf16_f32 v233, v26, v27
	ds_read_b64 v[96:97], v217 offset:16384
	ds_read_b64 v[98:99], v218 offset:16384
	ds_read_b64 v[100:101], v219 offset:16384
	ds_read_b64 v[102:103], v220 offset:16384
	ds_read_b64 v[104:105], v217 offset:18432
	ds_read_b64 v[106:107], v218 offset:18432
	ds_read_b64 v[108:109], v219 offset:18432
	ds_read_b64 v[110:111], v220 offset:18432
	s_waitcnt lgkmcnt(6)
	v_mfma_f32_16x16x32_bf16 v[96:99], v[194:197], v[96:99], v[112:115]
	s_waitcnt lgkmcnt(4)
	v_mfma_f32_16x16x32_bf16 v[96:99], v[230:233], v[100:103], v[96:99]
	s_nop 0
	ds_read_b64 v[112:113], v217 offset:20480
	ds_read_b64 v[114:115], v218 offset:20480
	ds_read_b64 v[234:235], v219 offset:20480
	ds_read_b64 v[236:237], v220 offset:20480
	s_waitcnt lgkmcnt(6)
	v_mfma_f32_16x16x32_bf16 v[100:103], v[194:197], v[104:107], v[116:119]
	s_waitcnt lgkmcnt(4)
	v_mfma_f32_16x16x32_bf16 v[100:103], v[230:233], v[108:111], v[100:103]
	ds_read_b64 v[108:109], v217 offset:22528
	ds_read_b64 v[110:111], v218 offset:22528
	ds_read_b64 v[116:117], v219 offset:22528
	ds_read_b64 v[118:119], v220 offset:22528
	s_waitcnt lgkmcnt(6)
	v_mfma_f32_16x16x32_bf16 v[104:107], v[194:197], v[112:115], v[120:123]
	s_waitcnt lgkmcnt(4)
	v_mfma_f32_16x16x32_bf16 v[104:107], v[230:233], v[234:237], v[104:107]
	ds_read_b64 v[112:113], v217 offset:24576
	ds_read_b64 v[114:115], v218 offset:24576
	ds_read_b64 v[120:121], v219 offset:24576
	ds_read_b64 v[122:123], v220 offset:24576
	s_waitcnt lgkmcnt(6)
	v_mfma_f32_16x16x32_bf16 v[108:111], v[194:197], v[108:111], v[124:127]
	s_waitcnt lgkmcnt(4)
	v_mfma_f32_16x16x32_bf16 v[108:111], v[230:233], v[116:119], v[108:111]
	ds_read_b64 v[116:117], v217 offset:26624
	ds_read_b64 v[118:119], v218 offset:26624
	ds_read_b64 v[124:125], v219 offset:26624
	ds_read_b64 v[126:127], v220 offset:26624
	s_waitcnt lgkmcnt(6)
	v_mfma_f32_16x16x32_bf16 v[112:115], v[194:197], v[112:115], v[128:131]
	s_waitcnt lgkmcnt(4)
	v_mfma_f32_16x16x32_bf16 v[112:115], v[230:233], v[120:123], v[112:115]
	ds_read_b64 v[120:121], v217 offset:28672
	ds_read_b64 v[122:123], v218 offset:28672
	ds_read_b64 v[128:129], v219 offset:28672
	ds_read_b64 v[130:131], v220 offset:28672
	s_waitcnt lgkmcnt(6)
	v_mfma_f32_16x16x32_bf16 v[116:119], v[194:197], v[116:119], v[132:135]
	s_waitcnt lgkmcnt(4)
	v_mfma_f32_16x16x32_bf16 v[116:119], v[230:233], v[124:127], v[116:119]
	ds_read_b64 v[124:125], v217 offset:30720
	ds_read_b64 v[126:127], v218 offset:30720
	ds_read_b64 v[132:133], v219 offset:30720
	ds_read_b64 v[134:135], v220 offset:30720
	s_waitcnt lgkmcnt(6)
	v_mfma_f32_16x16x32_bf16 v[120:123], v[194:197], v[120:123], v[136:139]
	s_waitcnt lgkmcnt(4)
	v_mfma_f32_16x16x32_bf16 v[120:123], v[230:233], v[128:131], v[120:123]
	s_waitcnt lgkmcnt(2)
	v_mfma_f32_16x16x32_bf16 v[124:127], v[194:197], v[124:127], v[140:143]
	s_waitcnt lgkmcnt(0)
	v_mfma_f32_16x16x32_bf16 v[124:127], v[230:233], v[132:135], v[124:127]
	ds_read_b64_tr_b16 v[128:129], v221 offset:49152
	ds_read_b64_tr_b16 v[130:131], v222 offset:49664
	ds_read_b64_tr_b16 v[132:133], v221 offset:53248
	ds_read_b64_tr_b16 v[134:135], v222 offset:53760
	ds_read_b64_tr_b16 v[136:137], v221 offset:57344
	ds_read_b64_tr_b16 v[138:139], v222 offset:57856
	v_mul_f32_e32 v30, v144, v30
	v_mul_f32_e32 v31, v145, v31
	v_mul_f32_e32 v28, v146, v28
	v_mul_f32_e32 v29, v147, v29
	ds_read_b64_tr_b16 v[140:141], v221 offset:61440
	ds_read_b64_tr_b16 v[142:143], v222 offset:61952
	ds_read_b64_tr_b16 v[194:195], v223 offset:49152
	ds_read_b64_tr_b16 v[196:197], v224 offset:49664
	ds_read_b64_tr_b16 v[230:231], v223 offset:53248
	ds_read_b64_tr_b16 v[232:233], v224 offset:53760
	ds_read_b64_tr_b16 v[234:235], v223 offset:57344
	ds_read_b64_tr_b16 v[236:237], v224 offset:57856
	ds_read_b64_tr_b16 v[238:239], v223 offset:61440
	ds_read_b64_tr_b16 v[240:241], v224 offset:61952
	s_waitcnt lgkmcnt(14)
	v_mfma_f32_16x16x32_bf16 v[28:31], v[128:131], v[72:75], v[28:31]
	v_mul_f32_e32 v22, v144, v22
	v_mul_f32_e32 v23, v145, v23
	v_mul_f32_e32 v20, v146, v20
	v_mul_f32_e32 v21, v147, v21
	v_mul_f32_e32 v18, v144, v18
	v_mul_f32_e32 v19, v145, v19
	s_waitcnt lgkmcnt(12)
	v_mfma_f32_16x16x32_bf16 v[28:31], v[132:135], v[80:83], v[28:31]
	v_mul_f32_e32 v16, v146, v16
	v_mul_f32_e32 v17, v147, v17
	v_mul_f32_e32 v26, v144, v26
	v_mul_f32_e32 v27, v145, v27
	v_mul_f32_e32 v24, v146, v24
	v_mul_f32_e32 v25, v147, v25
	s_waitcnt lgkmcnt(10)
	v_mfma_f32_16x16x32_bf16 v[28:31], v[136:139], v[88:91], v[28:31]
	s_andn2_b64 vcc, exec, s[22:23]
	s_waitcnt lgkmcnt(8)
	v_mfma_f32_16x16x32_bf16 v[28:31], v[140:143], v[92:95], v[28:31]
	ds_read_b64_tr_b16 v[128:129], v225 offset:49152
	ds_read_b64_tr_b16 v[130:131], v226 offset:49664
	ds_read_b64_tr_b16 v[132:133], v225 offset:53248
	ds_read_b64_tr_b16 v[134:135], v226 offset:53760
	ds_read_b64_tr_b16 v[136:137], v225 offset:57344
	ds_read_b64_tr_b16 v[138:139], v226 offset:57856
	ds_read_b64_tr_b16 v[140:141], v225 offset:61440
	ds_read_b64_tr_b16 v[142:143], v226 offset:61952
	s_waitcnt lgkmcnt(14)
	v_mfma_f32_16x16x32_bf16 v[20:23], v[194:197], v[72:75], v[20:23]
	s_waitcnt lgkmcnt(12)
	v_mfma_f32_16x16x32_bf16 v[20:23], v[230:233], v[80:83], v[20:23]
	s_waitcnt lgkmcnt(10)
	v_mfma_f32_16x16x32_bf16 v[20:23], v[234:237], v[88:91], v[20:23]
	s_waitcnt lgkmcnt(8)
	v_mfma_f32_16x16x32_bf16 v[20:23], v[238:241], v[92:95], v[20:23]
	ds_read_b64_tr_b16 v[194:195], v227 offset:49152
	ds_read_b64_tr_b16 v[196:197], v228 offset:49664
	ds_read_b64_tr_b16 v[230:231], v227 offset:53248
	ds_read_b64_tr_b16 v[232:233], v228 offset:53760
	ds_read_b64_tr_b16 v[234:235], v227 offset:57344
	ds_read_b64_tr_b16 v[236:237], v228 offset:57856
	ds_read_b64_tr_b16 v[238:239], v227 offset:61440
	ds_read_b64_tr_b16 v[240:241], v228 offset:61952
	s_waitcnt lgkmcnt(14)
	v_mfma_f32_16x16x32_bf16 v[16:19], v[128:131], v[72:75], v[16:19]
	s_waitcnt lgkmcnt(0)
	s_barrier
	v_cndmask_b32_e64 v128, 0, 1, s[22:23]
	v_cmp_ne_u32_e64 s[34:35], 1, v128
	s_waitcnt lgkmcnt(12)
	v_mfma_f32_16x16x32_bf16 v[16:19], v[132:135], v[80:83], v[16:19]
	s_cbranch_vccnz .Lscan1_nodma
	s_waitcnt vmcnt(8)
	s_branch .Lscan1_wdone

; __device__ __forceinline__ void scan_phase(const Frame& F, const bf16_t* Q, const bf16_t* K, const bf16_t* V, const bf16_t* PB, bf16_t* OF, bf16_t* OB, int half) {
;     ...
;                 {
;                     bf16x8 Rf[2];
; #pragma unroll
;                     for (int ks = 0; ks < 2; ++ks) { const f32x4 r0v = Rt[4 * p + 2 * ks], r1v = Rt[4 * p + 2 * ks + 1];
;                         const u32x4 wvv = {cvt_pk_bf16(r0v[0], r0v[1]), cvt_pk_bf16(r0v[2], r0v[3]), cvt_pk_bf16(r1v[0], r1v[1]), cvt_pk_bf16(r1v[2], r1v[3])};
;                         Rf[ks] = __builtin_bit_cast(bf16x8, wvv); }
;                     u32x4 qf[2][2];
;     ...
;                     SCAN_QREAD(0, 0);
; #pragma unroll
;                     for (int it = 0; it < 8; ++it) { if (it < 7) SCAN_QREAD((it + 1) & 1, it + 1);
; #pragma unroll
;                         for (int ks = 0; ks < 2; ++ks) Ot[it] = __builtin_amdgcn_mfma_f32_16x16x32_bf16(Rf[ks], __builtin_bit_cast(bf16x8, qf[it & 1][ks]), Ot[it], 0, 0, 0); }
;     ...
;                     __builtin_amdgcn_sched_group_barrier(0x100, 4, 0);
;                     __builtin_amdgcn_sched_group_barrier(0x100, 4, 0); __builtin_amdgcn_sched_group_barrier(0x8, 2, 0);
;                     __builtin_amdgcn_sched_group_barrier(0x100, 4, 0); __builtin_amdgcn_sched_group_barrier(0x8, 2, 0);
;                     __builtin_amdgcn_sched_group_barrier(0x100, 4, 0); __builtin_amdgcn_sched_group_barrier(0x8, 2, 0);
;                     __builtin_amdgcn_sched_group_barrier(0x100, 4, 0); __builtin_amdgcn_sched_group_barrier(0x8, 2, 0);
;                     __builtin_amdgcn_sched_group_barrier(0x100, 4, 0); __builtin_amdgcn_sched_group_barrier(0x8, 2, 0);
;                     __builtin_amdgcn_sched_group_barrier(0x100, 4, 0); __builtin_amdgcn_sched_group_barrier(0x8, 2, 0);
;                     __builtin_amdgcn_sched_group_barrier(0x100, 4, 0); __builtin_amdgcn_sched_group_barrier(0x8, 2, 0);
;                     __builtin_amdgcn_sched_group_barrier(0x8, 2, 0);
;                 }
;                 __builtin_amdgcn_sched_barrier(0);
;                 { s16x4 kl[2][4], kh[2][4];
;     ...
;                 SCAN_KREAD(0, 0);
; #pragma unroll
;                 for (int mt = 0; mt < 4; ++mt) { if (mt < 3) SCAN_KREAD((mt + 1) & 1, mt + 1);
;                     f32x4 acc = Rt[4 * p + mt] * c1;
; #pragma unroll
.LBB0_992:
	v_cvt_pk_bf16_f32 v128, v12, v13
	v_cvt_pk_bf16_f32 v129, v14, v15
	v_cvt_pk_bf16_f32 v130, v8, v9
	v_cvt_pk_bf16_f32 v131, v10, v11
	v_cvt_pk_bf16_f32 v132, v4, v5
	v_cvt_pk_bf16_f32 v133, v6, v7
	v_cvt_pk_bf16_f32 v134, v0, v1
	v_cvt_pk_bf16_f32 v135, v2, v3
	ds_read_b64 v[136:137], v217
	ds_read_b64 v[138:139], v218
	ds_read_b64 v[140:141], v219
	ds_read_b64 v[142:143], v220
	ds_read_b64 v[194:195], v217 offset:2048
	ds_read_b64 v[196:197], v218 offset:2048
	ds_read_b64 v[230:231], v219 offset:2048
	ds_read_b64 v[232:233], v220 offset:2048
	s_waitcnt lgkmcnt(6)
	v_mfma_f32_16x16x32_bf16 v[96:99], v[128:131], v[136:139], v[96:99]
	s_waitcnt lgkmcnt(4)
	v_mfma_f32_16x16x32_bf16 v[96:99], v[132:135], v[140:143], v[96:99]
	ds_read_b64 v[136:137], v217 offset:4096
	ds_read_b64 v[138:139], v218 offset:4096
	ds_read_b64 v[140:141], v219 offset:4096
	ds_read_b64 v[142:143], v220 offset:4096
	s_waitcnt lgkmcnt(6)
	v_mfma_f32_16x16x32_bf16 v[100:103], v[128:131], v[194:197], v[100:103]
	s_waitcnt lgkmcnt(4)
	v_mfma_f32_16x16x32_bf16 v[100:103], v[132:135], v[230:233], v[100:103]
	ds_read_b64 v[194:195], v217 offset:6144
	ds_read_b64 v[196:197], v218 offset:6144
	ds_read_b64 v[230:231], v219 offset:6144
	ds_read_b64 v[232:233], v220 offset:6144
	s_waitcnt lgkmcnt(6)
	v_mfma_f32_16x16x32_bf16 v[104:107], v[128:131], v[136:139], v[104:107]
	s_waitcnt lgkmcnt(4)
	v_mfma_f32_16x16x32_bf16 v[104:107], v[132:135], v[140:143], v[104:107]
	ds_read_b64 v[136:137], v217 offset:8192
	ds_read_b64 v[138:139], v218 offset:8192
	ds_read_b64 v[140:141], v219 offset:8192
	ds_read_b64 v[142:143], v220 offset:8192
	s_waitcnt lgkmcnt(6)
	v_mfma_f32_16x16x32_bf16 v[108:111], v[128:131], v[194:197], v[108:111]
	s_waitcnt lgkmcnt(4)
	v_mfma_f32_16x16x32_bf16 v[108:111], v[132:135], v[230:233], v[108:111]
	ds_read_b64 v[194:195], v217 offset:10240
	ds_read_b64 v[196:197], v218 offset:10240
	ds_read_b64 v[230:231], v219 offset:10240
	ds_read_b64 v[232:233], v220 offset:10240
	s_waitcnt lgkmcnt(6)
	v_mfma_f32_16x16x32_bf16 v[112:115], v[128:131], v[136:139], v[112:115]
	s_waitcnt lgkmcnt(4)
	v_mfma_f32_16x16x32_bf16 v[112:115], v[132:135], v[140:143], v[112:115]
	ds_read_b64 v[136:137], v217 offset:12288
	ds_read_b64 v[138:139], v218 offset:12288
	ds_read_b64 v[140:141], v219 offset:12288
	ds_read_b64 v[142:143], v220 offset:12288
	s_waitcnt lgkmcnt(6)
	v_mfma_f32_16x16x32_bf16 v[116:119], v[128:131], v[194:197], v[116:119]
	s_waitcnt lgkmcnt(4)
	v_mfma_f32_16x16x32_bf16 v[116:119], v[132:135], v[230:233], v[116:119]
	ds_read_b64 v[194:195], v217 offset:14336
	ds_read_b64 v[196:197], v218 offset:14336
	ds_read_b64 v[230:231], v219 offset:14336
	ds_read_b64 v[232:233], v220 offset:14336
	s_waitcnt lgkmcnt(6)
	v_mfma_f32_16x16x32_bf16 v[120:123], v[128:131], v[136:139], v[120:123]
	s_waitcnt lgkmcnt(4)
	v_mfma_f32_16x16x32_bf16 v[120:123], v[132:135], v[140:143], v[120:123]
	s_waitcnt lgkmcnt(2)
	v_mfma_f32_16x16x32_bf16 v[124:127], v[128:131], v[194:197], v[124:127]
	s_waitcnt lgkmcnt(0)
	v_mfma_f32_16x16x32_bf16 v[124:127], v[132:135], v[230:233], v[124:127]
	ds_read_b64_tr_b16 v[128:129], v221 offset:32768
	ds_read_b64_tr_b16 v[130:131], v222 offset:33280
	ds_read_b64_tr_b16 v[132:133], v221 offset:36864
	ds_read_b64_tr_b16 v[134:135], v222 offset:37376
	v_mov_b32_e32 v145, v144
	ds_read_b64_tr_b16 v[136:137], v221 offset:40960
	ds_read_b64_tr_b16 v[138:139], v222 offset:41472
	v_mul_f32_e32 v14, v144, v14
	v_mul_f32_e32 v15, v145, v15
	v_mul_f32_e32 v12, v146, v12
	v_mul_f32_e32 v13, v147, v13
	ds_read_b64_tr_b16 v[140:141], v221 offset:45056
	ds_read_b64_tr_b16 v[142:143], v222 offset:45568
	ds_read_b64_tr_b16 v[194:195], v223 offset:32768
	ds_read_b64_tr_b16 v[196:197], v224 offset:33280
	ds_read_b64_tr_b16 v[230:231], v223 offset:36864
	ds_read_b64_tr_b16 v[232:233], v224 offset:37376
	ds_read_b64_tr_b16 v[234:235], v223 offset:40960
	ds_read_b64_tr_b16 v[236:237], v224 offset:41472
	ds_read_b64_tr_b16 v[238:239], v223 offset:45056
	ds_read_b64_tr_b16 v[240:241], v224 offset:45568
	s_waitcnt lgkmcnt(14)
	v_mfma_f32_16x16x32_bf16 v[12:15], v[128:131], v[72:75], v[12:15]
	v_mul_f32_e32 v10, v144, v10
	v_mul_f32_e32 v11, v145, v11
	v_mul_f32_e32 v8, v146, v8
	v_mul_f32_e32 v9, v147, v9
	v_mul_f32_e32 v6, v144, v6
	v_mul_f32_e32 v7, v145, v7
	s_waitcnt lgkmcnt(12)
	v_mfma_f32_16x16x32_bf16 v[12:15], v[132:135], v[80:83], v[12:15]
	v_mul_f32_e32 v4, v146, v4
	v_mul_f32_e32 v5, v147, v5
	v_mul_f32_e32 v2, v144, v2
	v_mul_f32_e32 v3, v145, v3
	v_mul_f32_e32 v0, v146, v0
	v_mul_f32_e32 v1, v147, v1
	s_waitcnt lgkmcnt(10)
	v_mfma_f32_16x16x32_bf16 v[12:15], v[136:139], v[88:91], v[12:15]
	s_and_b64 vcc, exec, s[34:35]
	s_waitcnt lgkmcnt(8)
	v_mfma_f32_16x16x32_bf16 v[12:15], v[140:143], v[92:95], v[12:15]
	ds_read_b64_tr_b16 v[128:129], v225 offset:32768
	ds_read_b64_tr_b16 v[130:131], v226 offset:33280
	ds_read_b64_tr_b16 v[132:133], v225 offset:36864
	ds_read_b64_tr_b16 v[134:135], v226 offset:37376
	ds_read_b64_tr_b16 v[136:137], v225 offset:40960
	ds_read_b64_tr_b16 v[138:139], v226 offset:41472
	ds_read_b64_tr_b16 v[140:141], v225 offset:45056
	ds_read_b64_tr_b16 v[142:143], v226 offset:45568
	s_waitcnt lgkmcnt(14)
	v_mfma_f32_16x16x32_bf16 v[8:11], v[194:197], v[72:75], v[8:11]
	s_waitcnt lgkmcnt(12)
	v_mfma_f32_16x16x32_bf16 v[8:11], v[230:233], v[80:83], v[8:11]
	s_waitcnt lgkmcnt(10)
	v_mfma_f32_16x16x32_bf16 v[8:11], v[234:237], v[88:91], v[8:11]
	s_waitcnt lgkmcnt(8)
	v_mfma_f32_16x16x32_bf16 v[8:11], v[238:241], v[92:95], v[8:11]
	ds_read_b64_tr_b16 v[194:195], v227 offset:32768
	ds_read_b64_tr_b16 v[196:197], v228 offset:33280
	ds_read_b64_tr_b16 v[230:231], v227 offset:36864
	ds_read_b64_tr_b16 v[232:233], v228 offset:37376
	ds_read_b64_tr_b16 v[234:235], v227 offset:40960
	ds_read_b64_tr_b16 v[236:237], v228 offset:41472
	ds_read_b64_tr_b16 v[238:239], v227 offset:45056
	ds_read_b64_tr_b16 v[240:241], v228 offset:45568
	s_waitcnt lgkmcnt(14)
	v_mfma_f32_16x16x32_bf16 v[4:7], v[128:131], v[72:75], v[4:7]
	s_waitcnt lgkmcnt(0)
	s_barrier
; __device__ __forceinline__ bf16x8 pack8(s16x4 lo, s16x4 hi) { return (bf16x8){lo[0], lo[1], lo[2], lo[3], hi[0], hi[1], hi[2], hi[3]}; }
; #define SCAN_LOAD_QK(cc, pq) do { const size_t u0_ = (rb + (size_t)(cc) * 128) * 2048 + head * 256 + (pq) * 64;     \
;             _Pragma("unroll") for (int ii = 0; ii < 2; ++ii) { rq[ii] = *(const GAS u32x4*)(Q + u0_ + (size_t)ii * 64 * 2048 + lqk_l); rk[ii] = *(const GAS u32x4*)(K + u0_ + (size_t)ii * 64 * 2048 + lqk_l); } } while (0)
; #define SCAN_WRITE_QK(par) do { _Pragma("unroll") for (int ii = 0; ii < 2; ++ii) { *(LAS u32x4*)(bSt + ((par) ? LQ1 : LQ0) + ii * 64 * QS) = rq[ii]; *(LAS u32x4*)(bSt + ((par) ? LK1 : LK0) + ii * 64 * QS) = rk[ii]; } } while (0)
; #define SCAN_KREAD(b_, mt_) do { _Pragma("unroll") for (int ks = 0; ks < 4; ++ks) { const int ko = ((p & 1) ? LK1 : LK0) + 32 * ks * QS; kl[b_][ks] = tr_read(bKlo[mt_] + ko); kh[b_][ks] = tr_read(bKhi[mt_] + ko); } } while (0)
; __device__ __forceinline__ void scan_phase(const Frame& F, const bf16_t* Q, const bf16_t* K, const bf16_t* V, const bf16_t* PB, bf16_t* OF, bf16_t* OB, int half) {
;     ...
;                 if (p < 3 || more) SCAN_WRITE_QK((p + 1) & 1);
;                 if (p == 1 && more) SCAN_DMA_VP(cn);
;                 if (p < 2) SCAN_LOAD_QK(c, p + 2); else if (more) SCAN_LOAD_QK(cn, p - 2);
;     ...
;                 for (int mt = 0; mt < 4; ++mt) { if (mt < 3) SCAN_KREAD((mt + 1) & 1, mt + 1);
;                     f32x4 acc = Rt[4 * p + mt] * c1;
; #pragma unroll
;                     for (int ks = 0; ks < 4; ++ks) acc = __builtin_amdgcn_mfma_f32_16x16x32_bf16(pack8(kl[mt & 1][ks], kh[mt & 1][ks]), Vf[ks], acc, 0, 0, 0);
;                     Rt[4 * p + mt] = acc; }
;     ...
;                 __builtin_amdgcn_sched_group_barrier(0x100, 8, 0);
;                 __builtin_amdgcn_sched_group_barrier(0x100, 8, 0); __builtin_amdgcn_sched_group_barrier(0x8, 4, 0);
;                 __builtin_amdgcn_sched_group_barrier(0x100, 8, 0); __builtin_amdgcn_sched_group_barrier(0x8, 4, 0);
;                 __builtin_amdgcn_sched_group_barrier(0x100, 8, 0); __builtin_amdgcn_sched_group_barrier(0x8, 4, 0);
;                 __builtin_amdgcn_sched_group_barrier(0x8, 4, 0);
;                 }
	s_waitcnt lgkmcnt(12)
	v_mfma_f32_16x16x32_bf16 v[4:7], v[132:135], v[80:83], v[4:7]
	s_waitcnt lgkmcnt(10)
	v_mfma_f32_16x16x32_bf16 v[4:7], v[136:139], v[88:91], v[4:7]
	s_waitcnt lgkmcnt(8)
	v_mfma_f32_16x16x32_bf16 v[4:7], v[140:143], v[92:95], v[4:7]
	s_waitcnt lgkmcnt(6)
	v_mfma_f32_16x16x32_bf16 v[0:3], v[194:197], v[72:75], v[0:3]
	s_waitcnt lgkmcnt(4)
	v_mfma_f32_16x16x32_bf16 v[0:3], v[230:233], v[80:83], v[0:3]
	s_waitcnt lgkmcnt(2)
	v_mfma_f32_16x16x32_bf16 v[0:3], v[234:237], v[88:91], v[0:3]
	s_waitcnt lgkmcnt(0)
	v_mfma_f32_16x16x32_bf16 v[0:3], v[238:241], v[92:95], v[0:3]
	s_cbranch_vccnz .LBB0_987
	s_waitcnt vmcnt(3)
	ds_write_b128 v214, v[64:67]
	s_waitcnt vmcnt(2)
	ds_write_b128 v214, v[68:71] offset:32768
	s_waitcnt vmcnt(1)
	ds_write_b128 v214, v[76:79] offset:8192
	s_waitcnt vmcnt(0)
	ds_write_b128 v214, v[84:87] offset:40960
	v_add_co_u32_e32 v64, vcc, 0x10880000, v152
	s_nop 1
	v_addc_co_u32_e32 v65, vcc, 0, v153, vcc
	v_add_co_u32_e32 v68, vcc, 0x4a980000, v150
	global_load_dwordx4 v[64:67], v[64:65], off offset:128
	s_nop 0
	v_addc_co_u32_e32 v69, vcc, 0, v151, vcc
	v_add_co_u32_e32 v76, vcc, 0x108c0000, v152
	global_load_dwordx4 v[68:71], v[68:69], off offset:128
	s_nop 0
	v_addc_co_u32_e32 v77, vcc, 0, v153, vcc
	v_add_co_u32_e32 v84, vcc, 0x4a9c0000, v150
	global_load_dwordx4 v[76:79], v[76:77], off offset:128
	s_nop 0
	v_addc_co_u32_e32 v85, vcc, 0, v151, vcc
	global_load_dwordx4 v[84:87], v[84:85], off offset:128
	s_branch .LBB0_987
